# v32 + waits that guarded only the replaced per-row loads removed from the GLU/RETQKV/GLA epilogues
# speedup vs baseline: 1.0283x; 1.0021x over previous
; DI unsigned pk(float lo, float hi) { f32x2 v = {lo, hi}; bf2_t b = __builtin_convertvector(v, bf2_t); return __builtin_bit_cast(unsigned, b); }
; DI float sigmoidf_(float x) { return 1.0f / (1.0f + __expf(-x)); }
; DI void gemm_epilogue(const GemmDesc& g, f32x4 (&acc)[2][2][4][2], int brow, int bcol, int wr, int wc, int fr, int fq) {
;     ...
;     const int ca = 128 * (bcol >> 8) + wc * 32 + 8 * fq;
;     const f32x4 ba0 = gld<f32x4>(g.bias + ca), ba1 = gld<f32x4>(g.bias + ca + 4);
;     const f32x4 bg0 = gld<f32x4>(g.bias + 1024 + ca), bg1 = gld<f32x4>(g.bias + 1024 + ca + 4);
; #pragma unroll
;     for (int ai = 0; ai < 2; ++ai)
; #pragma unroll
;       for (int m = 0; m < 4; ++m) {
;         const int row = rowb + ai * HALF + m * 16;
;         const float ru = gld<float>(g.rowscale + row);
;         const f32x4 a0 = acc[ai][0][m][0] * ru + ba0, a1 = acc[ai][0][m][1] * ru + ba1, t0 = acc[ai][1][m][0] * ru + bg0, t1 = acc[ai][1][m][1] * ru + bg1;
;         float o[8];
; #pragma unroll
;         for (int j = 0; j < 4; ++j) { o[j] = a0[j] * sigmoidf_(t0[j]); o[4 + j] = a1[j] * sigmoidf_(t1[j]); }
;         u32x4 w; w.x = pk(o[0], o[1]); w.y = pk(o[2], o[3]); w.z = pk(o[4], o[5]); w.w = pk(o[6], o[7]);
;         gst<u32x4>(g.o0 + (size_t)row * 1024 + ca, w);
.LBB0_135:
	s_lshl_b32 s86, s5, 8
	v_lshl_add_u32 v166, s50, 8, v218
	v_or_b32_e32 v164, s86, v158
	s_mov_b64 s[26:27], -1
	s_and_b64 vcc, exec, s[54:55]
	s_cbranch_vccz .LBB0_144
	s_mov_b64 s[48:49], 0
	s_cmp_lt_i32 s92, 3
	s_mov_b64 s[50:51], 0
	s_cbranch_scc1 .LBB0_147
	s_cmp_gt_i32 s92, 3
	s_cbranch_scc0 .LBB0_141
	s_cmp_eq_u32 s92, 4
	s_mov_b64 s[50:51], -1
	s_cbranch_scc0 .LBB0_140
	v_lshl_or_b32 v170, s5, 7, v158
	v_ashrrev_i32_e32 v171, 31, v170
	v_readlane_b32 s26, v255, 39
	v_lshlrev_b64 v[132:133], 2, v[170:171]
	v_readlane_b32 s27, v255, 40
	v_ashrrev_i32_e32 v167, 31, v166
	v_lshl_add_u64 v[134:135], s[76:77], 0, v[132:133]
	v_lshl_add_u64 v[140:141], s[26:27], 0, v[132:133]
	v_lshl_add_u64 v[168:169], v[166:167], 2, s[22:23]
	global_load_dwordx4 v[128:131], v[134:135], off offset:16
	global_load_dwordx4 v[136:139], v[134:135], off
	s_nop 0
	global_load_dwordx4 v[132:135], v[140:141], off offset:16
	s_nop 0
	global_load_dwordx4 v[140:143], v[140:141], off
	s_mov_b64 s[50:51], 0
	global_load_dword v236, v[168:169], off
	global_load_dword v237, v[168:169], off offset:64
	global_load_dword v238, v[168:169], off offset:128
	global_load_dword v239, v[168:169], off offset:192
	global_load_dword v240, v[168:169], off offset:512
	global_load_dword v241, v[168:169], off offset:576
	global_load_dword v242, v[168:169], off offset:640
	global_load_dword v243, v[168:169], off offset:704
	global_load_dword v148, v[168:169], off
	s_waitcnt vmcnt(0)
	v_fma_f32 v165, v60, v148, v140
	v_mul_f32_e32 v165, 0xbfb8aa3b, v165
	v_exp_f32_e32 v172, v165
	v_fma_f32 v165, v56, v148, v132
	v_mul_f32_e32 v165, 0xbfb8aa3b, v165
	v_exp_f32_e32 v174, v165
	v_fma_f32 v165, v61, v148, v141
	v_mul_f32_e32 v165, 0xbfb8aa3b, v165
	v_exp_f32_e32 v173, v165
	v_pk_fma_f32 v[176:177], v[124:125], v[148:149], v[136:137] op_sel_hi:[1,0,1]
	v_pk_add_f32 v[172:173], v[172:173], 1.0 op_sel_hi:[1,0]
	s_nop 0
	v_div_scale_f32 v165, s[26:27], v173, v173, 1.0
	v_rcp_f32_e32 v175, v165
	s_nop 0
	v_fma_f32 v178, -v165, v175, 1.0
	v_fmac_f32_e32 v175, v178, v175
	v_div_scale_f32 v178, vcc, 1.0, v173, 1.0
	v_mul_f32_e32 v179, v178, v175
	v_fma_f32 v180, -v165, v179, v178
	v_fmac_f32_e32 v179, v180, v175
	v_fma_f32 v165, -v165, v179, v178
	v_div_fmas_f32 v165, v165, v175, v179
	v_div_fixup_f32 v173, v165, v173, 1.0
	v_div_scale_f32 v165, s[26:27], v172, v172, 1.0
	v_rcp_f32_e32 v175, v165
	s_nop 0
	v_fma_f32 v178, -v165, v175, 1.0
	v_fmac_f32_e32 v175, v178, v175
	v_div_scale_f32 v178, vcc, 1.0, v172, 1.0
	v_mul_f32_e32 v179, v178, v175
	v_fma_f32 v180, -v165, v179, v178
	v_fmac_f32_e32 v179, v180, v175
	v_fma_f32 v165, -v165, v179, v178
	v_div_fmas_f32 v165, v165, v175, v179
	v_div_fixup_f32 v172, v165, v172, 1.0
	v_fma_f32 v165, v57, v148, v133
	v_mul_f32_e32 v165, 0xbfb8aa3b, v165
	v_exp_f32_e32 v175, v165
	v_pk_mul_f32 v[172:173], v[176:177], v[172:173]
	v_pk_fma_f32 v[176:177], v[120:121], v[148:149], v[128:129] op_sel_hi:[1,0,1]
	v_pk_add_f32 v[174:175], v[174:175], 1.0 op_sel_hi:[1,0]
	s_nop 0
	v_div_scale_f32 v165, s[26:27], v175, v175, 1.0
	v_rcp_f32_e32 v178, v165
	s_nop 0
	v_fma_f32 v179, -v165, v178, 1.0
	v_fmac_f32_e32 v178, v179, v178
	v_div_scale_f32 v179, vcc, 1.0, v175, 1.0
	v_mul_f32_e32 v180, v179, v178
	v_fma_f32 v181, -v165, v180, v179
	v_fmac_f32_e32 v180, v181, v178
	v_fma_f32 v165, -v165, v180, v179
	v_div_fmas_f32 v165, v165, v178, v180
	v_div_fixup_f32 v175, v165, v175, 1.0
	v_div_scale_f32 v165, s[26:27], v174, v174, 1.0
	v_rcp_f32_e32 v178, v165
	s_nop 0
	v_fma_f32 v179, -v165, v178, 1.0
	v_fmac_f32_e32 v178, v179, v178
	v_div_scale_f32 v179, vcc, 1.0, v174, 1.0
	v_mul_f32_e32 v180, v179, v178
	v_fma_f32 v181, -v165, v180, v179
	v_fmac_f32_e32 v180, v181, v178
	v_fma_f32 v165, -v165, v180, v179
	v_div_fmas_f32 v165, v165, v178, v180
	v_div_fixup_f32 v174, v165, v174, 1.0
	v_fma_f32 v165, v62, v148, v142
	v_mul_f32_e32 v165, 0xbfb8aa3b, v165
	v_exp_f32_e32 v180, v165
	v_fma_f32 v165, v58, v148, v134
	v_mul_f32_e32 v165, 0xbfb8aa3b, v165
	v_pk_mul_f32 v[174:175], v[176:177], v[174:175]
	v_exp_f32_e32 v176, v165
	v_fma_f32 v165, v63, v148, v143
	v_mul_f32_e32 v165, 0xbfb8aa3b, v165
	v_exp_f32_e32 v181, v165
	v_pk_fma_f32 v[178:179], v[126:127], v[148:149], v[138:139] op_sel_hi:[1,0,1]
	v_pk_add_f32 v[180:181], v[180:181], 1.0 op_sel_hi:[1,0]
	s_nop 0
	v_div_scale_f32 v165, s[26:27], v181, v181, 1.0
	v_rcp_f32_e32 v177, v165
	s_nop 0
	v_fma_f32 v182, -v165, v177, 1.0
	v_fmac_f32_e32 v177, v182, v177
	v_div_scale_f32 v182, vcc, 1.0, v181, 1.0
	v_mul_f32_e32 v183, v182, v177
	v_fma_f32 v184, -v165, v183, v182
	v_fmac_f32_e32 v183, v184, v177
	v_fma_f32 v165, -v165, v183, v182
	v_div_fmas_f32 v165, v165, v177, v183
	v_div_fixup_f32 v181, v165, v181, 1.0
	v_div_scale_f32 v165, s[26:27], v180, v180, 1.0
	v_rcp_f32_e32 v177, v165
	s_nop 0
	v_fma_f32 v182, -v165, v177, 1.0
	v_fmac_f32_e32 v177, v182, v177
	v_div_scale_f32 v182, vcc, 1.0, v180, 1.0
	v_mul_f32_e32 v183, v182, v177
	v_fma_f32 v184, -v165, v183, v182
	v_fmac_f32_e32 v183, v184, v177
	v_fma_f32 v165, -v165, v183, v182
	v_div_fmas_f32 v165, v165, v177, v183
	v_div_fixup_f32 v180, v165, v180, 1.0
	v_fma_f32 v165, v59, v148, v135
	v_mul_f32_e32 v165, 0xbfb8aa3b, v165
	v_exp_f32_e32 v177, v165
	v_pk_mul_f32 v[178:179], v[178:179], v[180:181]
	v_pk_fma_f32 v[180:181], v[122:123], v[148:149], v[130:131] op_sel_hi:[1,0,1]
	v_pk_add_f32 v[176:177], v[176:177], 1.0 op_sel_hi:[1,0]
	s_nop 0
	v_div_scale_f32 v148, s[26:27], v177, v177, 1.0
	v_rcp_f32_e32 v165, v148
	s_nop 0
	v_fma_f32 v182, -v148, v165, 1.0
	v_fmac_f32_e32 v165, v182, v165
	v_div_scale_f32 v182, vcc, 1.0, v177, 1.0
	v_mul_f32_e32 v183, v182, v165
; DI unsigned pk(float lo, float hi) { f32x2 v = {lo, hi}; bf2_t b = __builtin_convertvector(v, bf2_t); return __builtin_bit_cast(unsigned, b); }
; DI float sigmoidf_(float x) { return 1.0f / (1.0f + __expf(-x)); }
; DI void gemm_epilogue(const GemmDesc& g, f32x4 (&acc)[2][2][4][2], int brow, int bcol, int wr, int wc, int fr, int fq) {
;     ...
;     for (int ai = 0; ai < 2; ++ai)
; #pragma unroll
;       for (int m = 0; m < 4; ++m) {
;         const int row = rowb + ai * HALF + m * 16;
;         const float ru = gld<float>(g.rowscale + row);
;         const f32x4 a0 = acc[ai][0][m][0] * ru + ba0, a1 = acc[ai][0][m][1] * ru + ba1, t0 = acc[ai][1][m][0] * ru + bg0, t1 = acc[ai][1][m][1] * ru + bg1;
;         float o[8];
; #pragma unroll
;         for (int j = 0; j < 4; ++j) { o[j] = a0[j] * sigmoidf_(t0[j]); o[4 + j] = a1[j] * sigmoidf_(t1[j]); }
;         u32x4 w; w.x = pk(o[0], o[1]); w.y = pk(o[2], o[3]); w.z = pk(o[4], o[5]); w.w = pk(o[6], o[7]);
;         gst<u32x4>(g.o0 + (size_t)row * 1024 + ca, w);
	v_fma_f32 v184, -v148, v183, v182
	v_fmac_f32_e32 v183, v184, v165
	v_fma_f32 v148, -v148, v183, v182
	v_div_fmas_f32 v148, v148, v165, v183
	v_div_fixup_f32 v177, v148, v177, 1.0
	v_div_scale_f32 v148, s[26:27], v176, v176, 1.0
	v_rcp_f32_e32 v165, v148
	s_nop 0
	v_fma_f32 v182, -v148, v165, 1.0
	v_fmac_f32_e32 v165, v182, v165
	v_div_scale_f32 v182, vcc, 1.0, v176, 1.0
	v_mul_f32_e32 v183, v182, v165
	v_fma_f32 v184, -v148, v183, v182
	v_fmac_f32_e32 v183, v184, v165
	v_fma_f32 v148, -v148, v183, v182
	v_div_fmas_f32 v148, v148, v165, v183
	v_div_fixup_f32 v176, v148, v176, 1.0
	v_pk_mul_f32 v[180:181], v[180:181], v[176:177]
	v_cvt_pk_bf16_f32 v176, v172, v173
	v_lshlrev_b64 v[172:173], 11, v[166:167]
	v_cvt_pk_bf16_f32 v177, v178, v179
	v_cvt_pk_bf16_f32 v178, v174, v175
	v_lshl_add_u64 v[174:175], s[64:65], 0, v[172:173]
	v_lshlrev_b64 v[172:173], 1, v[170:171]
	v_cvt_pk_bf16_f32 v179, v180, v181
	v_lshl_add_u64 v[170:171], v[174:175], 0, v[172:173]
	global_store_dwordx4 v[170:171], v[176:179], off
	s_nop 1
	v_mov_b32_e32 v148, v237
	v_or_b32_e32 v174, 16, v166
	v_ashrrev_i32_e32 v175, 31, v174
	v_lshlrev_b64 v[174:175], 11, v[174:175]
	v_lshl_add_u64 v[174:175], s[64:65], 0, v[174:175]
	v_lshl_add_u64 v[174:175], v[174:175], 0, v[172:173]
	v_fma_f32 v165, v52, v148, v140
	v_mul_f32_e32 v165, 0xbfb8aa3b, v165
	v_exp_f32_e32 v176, v165
	v_fma_f32 v165, v48, v148, v132
	v_mul_f32_e32 v165, 0xbfb8aa3b, v165
	v_exp_f32_e32 v178, v165
	v_fma_f32 v165, v53, v148, v141
	v_mul_f32_e32 v165, 0xbfb8aa3b, v165
	v_exp_f32_e32 v177, v165
	v_pk_fma_f32 v[180:181], v[116:117], v[148:149], v[136:137] op_sel_hi:[1,0,1]
	v_pk_add_f32 v[176:177], v[176:177], 1.0 op_sel_hi:[1,0]
	s_nop 0
	v_div_scale_f32 v165, s[26:27], v177, v177, 1.0
	v_rcp_f32_e32 v167, v165
	s_nop 0
	v_fma_f32 v179, -v165, v167, 1.0
	v_fmac_f32_e32 v167, v179, v167
	v_div_scale_f32 v179, vcc, 1.0, v177, 1.0
	v_mul_f32_e32 v182, v179, v167
	v_fma_f32 v183, -v165, v182, v179
	v_fmac_f32_e32 v182, v183, v167
	v_fma_f32 v165, -v165, v182, v179
	v_div_fmas_f32 v165, v165, v167, v182
	v_div_fixup_f32 v177, v165, v177, 1.0
	v_div_scale_f32 v165, s[26:27], v176, v176, 1.0
	v_rcp_f32_e32 v167, v165
	s_nop 0
	v_fma_f32 v179, -v165, v167, 1.0
	v_fmac_f32_e32 v167, v179, v167
	v_div_scale_f32 v179, vcc, 1.0, v176, 1.0
	v_mul_f32_e32 v182, v179, v167
	v_fma_f32 v183, -v165, v182, v179
	v_fmac_f32_e32 v182, v183, v167
	v_fma_f32 v165, -v165, v182, v179
	v_div_fmas_f32 v165, v165, v167, v182
	v_div_fixup_f32 v176, v165, v176, 1.0
	v_fma_f32 v165, v49, v148, v133
	v_mul_f32_e32 v165, 0xbfb8aa3b, v165
	v_exp_f32_e32 v179, v165
	v_pk_mul_f32 v[176:177], v[180:181], v[176:177]
	v_pk_fma_f32 v[180:181], v[112:113], v[148:149], v[128:129] op_sel_hi:[1,0,1]
	v_cvt_pk_bf16_f32 v176, v176, v177
	v_pk_add_f32 v[178:179], v[178:179], 1.0 op_sel_hi:[1,0]
	s_nop 0
	v_div_scale_f32 v165, s[26:27], v179, v179, 1.0
	v_rcp_f32_e32 v167, v165
	s_nop 0
	v_fma_f32 v182, -v165, v167, 1.0
	v_fmac_f32_e32 v167, v182, v167
	v_div_scale_f32 v182, vcc, 1.0, v179, 1.0
	v_mul_f32_e32 v183, v182, v167
	v_fma_f32 v184, -v165, v183, v182
	v_fmac_f32_e32 v183, v184, v167
	v_fma_f32 v165, -v165, v183, v182
	v_div_fmas_f32 v165, v165, v167, v183
	v_div_fixup_f32 v179, v165, v179, 1.0
	v_div_scale_f32 v165, s[26:27], v178, v178, 1.0
	v_rcp_f32_e32 v167, v165
	s_nop 0
	v_fma_f32 v182, -v165, v167, 1.0
	v_fmac_f32_e32 v167, v182, v167
	v_div_scale_f32 v182, vcc, 1.0, v178, 1.0
	v_mul_f32_e32 v183, v182, v167
	v_fma_f32 v184, -v165, v183, v182
	v_fmac_f32_e32 v183, v184, v167
	v_fma_f32 v165, -v165, v183, v182
	v_div_fmas_f32 v165, v165, v167, v183
	v_div_fixup_f32 v178, v165, v178, 1.0
	v_fma_f32 v165, v54, v148, v142
	v_mul_f32_e32 v165, 0xbfb8aa3b, v165
	v_pk_mul_f32 v[178:179], v[180:181], v[178:179]
	v_exp_f32_e32 v180, v165
	v_fma_f32 v165, v50, v148, v134
	v_mul_f32_e32 v165, 0xbfb8aa3b, v165
	v_exp_f32_e32 v182, v165
	v_fma_f32 v165, v55, v148, v143
	v_mul_f32_e32 v165, 0xbfb8aa3b, v165
	v_exp_f32_e32 v181, v165
	v_pk_fma_f32 v[184:185], v[118:119], v[148:149], v[138:139] op_sel_hi:[1,0,1]
	v_cvt_pk_bf16_f32 v178, v178, v179
	v_pk_add_f32 v[180:181], v[180:181], 1.0 op_sel_hi:[1,0]
	s_nop 0
	v_div_scale_f32 v165, s[26:27], v181, v181, 1.0
	v_rcp_f32_e32 v167, v165
	s_nop 0
	v_fma_f32 v183, -v165, v167, 1.0
	v_fmac_f32_e32 v167, v183, v167
	v_div_scale_f32 v183, vcc, 1.0, v181, 1.0
	v_mul_f32_e32 v186, v183, v167
	v_fma_f32 v187, -v165, v186, v183
	v_fmac_f32_e32 v186, v187, v167
	v_fma_f32 v165, -v165, v186, v183
	v_div_fmas_f32 v165, v165, v167, v186
	v_div_fixup_f32 v181, v165, v181, 1.0
	v_div_scale_f32 v165, s[26:27], v180, v180, 1.0
	v_rcp_f32_e32 v167, v165
	s_nop 0
	v_fma_f32 v183, -v165, v167, 1.0
	v_fmac_f32_e32 v167, v183, v167
	v_div_scale_f32 v183, vcc, 1.0, v180, 1.0
	v_mul_f32_e32 v186, v183, v167
	v_fma_f32 v187, -v165, v186, v183
	v_fmac_f32_e32 v186, v187, v167
	v_fma_f32 v165, -v165, v186, v183
	v_div_fmas_f32 v165, v165, v167, v186
	v_div_fixup_f32 v180, v165, v180, 1.0
	v_fma_f32 v165, v51, v148, v135
	v_mul_f32_e32 v165, 0xbfb8aa3b, v165
	v_exp_f32_e32 v183, v165
	v_pk_mul_f32 v[180:181], v[184:185], v[180:181]
	v_pk_fma_f32 v[184:185], v[114:115], v[148:149], v[130:131] op_sel_hi:[1,0,1]
	v_cvt_pk_bf16_f32 v177, v180, v181
	v_pk_add_f32 v[182:183], v[182:183], 1.0 op_sel_hi:[1,0]
	s_nop 0
	v_div_scale_f32 v148, s[26:27], v183, v183, 1.0
	v_rcp_f32_e32 v165, v148
	s_nop 0
	v_fma_f32 v167, -v148, v165, 1.0
	v_fmac_f32_e32 v165, v167, v165
	v_div_scale_f32 v167, vcc, 1.0, v183, 1.0
	v_mul_f32_e32 v186, v167, v165
	v_fma_f32 v187, -v148, v186, v167
	v_fmac_f32_e32 v186, v187, v165
	v_fma_f32 v148, -v148, v186, v167
; DI unsigned pk(float lo, float hi) { f32x2 v = {lo, hi}; bf2_t b = __builtin_convertvector(v, bf2_t); return __builtin_bit_cast(unsigned, b); }
; DI float sigmoidf_(float x) { return 1.0f / (1.0f + __expf(-x)); }
; DI void gemm_epilogue(const GemmDesc& g, f32x4 (&acc)[2][2][4][2], int brow, int bcol, int wr, int wc, int fr, int fq) {
;     ...
;     for (int ai = 0; ai < 2; ++ai)
; #pragma unroll
;       for (int m = 0; m < 4; ++m) {
;         const int row = rowb + ai * HALF + m * 16;
;         const float ru = gld<float>(g.rowscale + row);
;         const f32x4 a0 = acc[ai][0][m][0] * ru + ba0, a1 = acc[ai][0][m][1] * ru + ba1, t0 = acc[ai][1][m][0] * ru + bg0, t1 = acc[ai][1][m][1] * ru + bg1;
;         float o[8];
; #pragma unroll
;         for (int j = 0; j < 4; ++j) { o[j] = a0[j] * sigmoidf_(t0[j]); o[4 + j] = a1[j] * sigmoidf_(t1[j]); }
;         u32x4 w; w.x = pk(o[0], o[1]); w.y = pk(o[2], o[3]); w.z = pk(o[4], o[5]); w.w = pk(o[6], o[7]);
;         gst<u32x4>(g.o0 + (size_t)row * 1024 + ca, w);
	v_div_fmas_f32 v148, v148, v165, v186
	v_div_fixup_f32 v183, v148, v183, 1.0
	v_div_scale_f32 v148, s[26:27], v182, v182, 1.0
	v_rcp_f32_e32 v165, v148
	s_nop 0
	v_fma_f32 v167, -v148, v165, 1.0
	v_fmac_f32_e32 v165, v167, v165
	v_div_scale_f32 v167, vcc, 1.0, v182, 1.0
	v_mul_f32_e32 v186, v167, v165
	v_fma_f32 v187, -v148, v186, v167
	v_fmac_f32_e32 v186, v187, v165
	v_fma_f32 v148, -v148, v186, v167
	v_div_fmas_f32 v148, v148, v165, v186
	v_div_fixup_f32 v182, v148, v182, 1.0
	v_pk_mul_f32 v[182:183], v[184:185], v[182:183]
	s_nop 0
	v_cvt_pk_bf16_f32 v179, v182, v183
	global_store_dwordx4 v[174:175], v[176:179], off
	s_nop 1
	v_mov_b32_e32 v148, v238
	v_or_b32_e32 v174, 32, v166
	v_ashrrev_i32_e32 v175, 31, v174
	v_lshlrev_b64 v[174:175], 11, v[174:175]
	v_lshl_add_u64 v[174:175], s[64:65], 0, v[174:175]
	v_lshl_add_u64 v[174:175], v[174:175], 0, v[172:173]
	v_fma_f32 v165, v44, v148, v140
	v_mul_f32_e32 v165, 0xbfb8aa3b, v165
	v_exp_f32_e32 v176, v165
	v_fma_f32 v165, v40, v148, v132
	v_mul_f32_e32 v165, 0xbfb8aa3b, v165
	v_exp_f32_e32 v178, v165
	v_fma_f32 v165, v45, v148, v141
	v_mul_f32_e32 v165, 0xbfb8aa3b, v165
	v_exp_f32_e32 v177, v165
	v_pk_fma_f32 v[180:181], v[108:109], v[148:149], v[136:137] op_sel_hi:[1,0,1]
	v_pk_add_f32 v[176:177], v[176:177], 1.0 op_sel_hi:[1,0]
	s_nop 0
	v_div_scale_f32 v165, s[26:27], v177, v177, 1.0
	v_rcp_f32_e32 v167, v165
	s_nop 0
	v_fma_f32 v179, -v165, v167, 1.0
	v_fmac_f32_e32 v167, v179, v167
	v_div_scale_f32 v179, vcc, 1.0, v177, 1.0
	v_mul_f32_e32 v182, v179, v167
	v_fma_f32 v183, -v165, v182, v179
	v_fmac_f32_e32 v182, v183, v167
	v_fma_f32 v165, -v165, v182, v179
	v_div_fmas_f32 v165, v165, v167, v182
	v_div_fixup_f32 v177, v165, v177, 1.0
	v_div_scale_f32 v165, s[26:27], v176, v176, 1.0
	v_rcp_f32_e32 v167, v165
	s_nop 0
	v_fma_f32 v179, -v165, v167, 1.0
	v_fmac_f32_e32 v167, v179, v167
	v_div_scale_f32 v179, vcc, 1.0, v176, 1.0
	v_mul_f32_e32 v182, v179, v167
	v_fma_f32 v183, -v165, v182, v179
	v_fmac_f32_e32 v182, v183, v167
	v_fma_f32 v165, -v165, v182, v179
	v_div_fmas_f32 v165, v165, v167, v182
	v_div_fixup_f32 v176, v165, v176, 1.0
	v_fma_f32 v165, v41, v148, v133
	v_mul_f32_e32 v165, 0xbfb8aa3b, v165
	v_exp_f32_e32 v179, v165
	v_pk_mul_f32 v[176:177], v[180:181], v[176:177]
	v_pk_fma_f32 v[180:181], v[104:105], v[148:149], v[128:129] op_sel_hi:[1,0,1]
	v_cvt_pk_bf16_f32 v176, v176, v177
	v_pk_add_f32 v[178:179], v[178:179], 1.0 op_sel_hi:[1,0]
	s_nop 0
	v_div_scale_f32 v165, s[26:27], v179, v179, 1.0
	v_rcp_f32_e32 v167, v165
	s_nop 0
	v_fma_f32 v182, -v165, v167, 1.0
	v_fmac_f32_e32 v167, v182, v167
	v_div_scale_f32 v182, vcc, 1.0, v179, 1.0
	v_mul_f32_e32 v183, v182, v167
	v_fma_f32 v184, -v165, v183, v182
	v_fmac_f32_e32 v183, v184, v167
	v_fma_f32 v165, -v165, v183, v182
	v_div_fmas_f32 v165, v165, v167, v183
	v_div_fixup_f32 v179, v165, v179, 1.0
	v_div_scale_f32 v165, s[26:27], v178, v178, 1.0
	v_rcp_f32_e32 v167, v165
	s_nop 0
	v_fma_f32 v182, -v165, v167, 1.0
	v_fmac_f32_e32 v167, v182, v167
	v_div_scale_f32 v182, vcc, 1.0, v178, 1.0
	v_mul_f32_e32 v183, v182, v167
	v_fma_f32 v184, -v165, v183, v182
	v_fmac_f32_e32 v183, v184, v167
	v_fma_f32 v165, -v165, v183, v182
	v_div_fmas_f32 v165, v165, v167, v183
	v_div_fixup_f32 v178, v165, v178, 1.0
	v_fma_f32 v165, v46, v148, v142
	v_mul_f32_e32 v165, 0xbfb8aa3b, v165
	v_pk_mul_f32 v[178:179], v[180:181], v[178:179]
	v_exp_f32_e32 v180, v165
	v_fma_f32 v165, v42, v148, v134
	v_mul_f32_e32 v165, 0xbfb8aa3b, v165
	v_exp_f32_e32 v182, v165
	v_fma_f32 v165, v47, v148, v143
	v_mul_f32_e32 v165, 0xbfb8aa3b, v165
	v_exp_f32_e32 v181, v165
	v_pk_fma_f32 v[184:185], v[110:111], v[148:149], v[138:139] op_sel_hi:[1,0,1]
	v_cvt_pk_bf16_f32 v178, v178, v179
	v_pk_add_f32 v[180:181], v[180:181], 1.0 op_sel_hi:[1,0]
	s_nop 0
	v_div_scale_f32 v165, s[26:27], v181, v181, 1.0
	v_rcp_f32_e32 v167, v165
	s_nop 0
	v_fma_f32 v183, -v165, v167, 1.0
	v_fmac_f32_e32 v167, v183, v167
	v_div_scale_f32 v183, vcc, 1.0, v181, 1.0
	v_mul_f32_e32 v186, v183, v167
	v_fma_f32 v187, -v165, v186, v183
	v_fmac_f32_e32 v186, v187, v167
	v_fma_f32 v165, -v165, v186, v183
	v_div_fmas_f32 v165, v165, v167, v186
	v_div_fixup_f32 v181, v165, v181, 1.0
	v_div_scale_f32 v165, s[26:27], v180, v180, 1.0
	v_rcp_f32_e32 v167, v165
	s_nop 0
	v_fma_f32 v183, -v165, v167, 1.0
	v_fmac_f32_e32 v167, v183, v167
	v_div_scale_f32 v183, vcc, 1.0, v180, 1.0
	v_mul_f32_e32 v186, v183, v167
	v_fma_f32 v187, -v165, v186, v183
	v_fmac_f32_e32 v186, v187, v167
	v_fma_f32 v165, -v165, v186, v183
	v_div_fmas_f32 v165, v165, v167, v186
	v_div_fixup_f32 v180, v165, v180, 1.0
	v_fma_f32 v165, v43, v148, v135
	v_mul_f32_e32 v165, 0xbfb8aa3b, v165
	v_exp_f32_e32 v183, v165
	v_pk_mul_f32 v[180:181], v[184:185], v[180:181]
	v_pk_fma_f32 v[184:185], v[106:107], v[148:149], v[130:131] op_sel_hi:[1,0,1]
	v_cvt_pk_bf16_f32 v177, v180, v181
	v_pk_add_f32 v[182:183], v[182:183], 1.0 op_sel_hi:[1,0]
	s_nop 0
	v_div_scale_f32 v148, s[26:27], v183, v183, 1.0
	v_rcp_f32_e32 v165, v148
	s_nop 0
	v_fma_f32 v167, -v148, v165, 1.0
	v_fmac_f32_e32 v165, v167, v165
	v_div_scale_f32 v167, vcc, 1.0, v183, 1.0
	v_mul_f32_e32 v186, v167, v165
	v_fma_f32 v187, -v148, v186, v167
	v_fmac_f32_e32 v186, v187, v165
	v_fma_f32 v148, -v148, v186, v167
	v_div_fmas_f32 v148, v148, v165, v186
	v_div_fixup_f32 v183, v148, v183, 1.0
	v_div_scale_f32 v148, s[26:27], v182, v182, 1.0
	v_rcp_f32_e32 v165, v148
	s_nop 0
	v_fma_f32 v167, -v148, v165, 1.0
	v_fmac_f32_e32 v165, v167, v165
	v_div_scale_f32 v167, vcc, 1.0, v182, 1.0
	v_mul_f32_e32 v186, v167, v165
	v_fma_f32 v187, -v148, v186, v167
	v_fmac_f32_e32 v186, v187, v165
; DI unsigned pk(float lo, float hi) { f32x2 v = {lo, hi}; bf2_t b = __builtin_convertvector(v, bf2_t); return __builtin_bit_cast(unsigned, b); }
; DI float sigmoidf_(float x) { return 1.0f / (1.0f + __expf(-x)); }
; DI void gemm_epilogue(const GemmDesc& g, f32x4 (&acc)[2][2][4][2], int brow, int bcol, int wr, int wc, int fr, int fq) {
;     ...
;     for (int ai = 0; ai < 2; ++ai)
; #pragma unroll
;       for (int m = 0; m < 4; ++m) {
;         const int row = rowb + ai * HALF + m * 16;
;         const float ru = gld<float>(g.rowscale + row);
;         const f32x4 a0 = acc[ai][0][m][0] * ru + ba0, a1 = acc[ai][0][m][1] * ru + ba1, t0 = acc[ai][1][m][0] * ru + bg0, t1 = acc[ai][1][m][1] * ru + bg1;
;         float o[8];
; #pragma unroll
;         for (int j = 0; j < 4; ++j) { o[j] = a0[j] * sigmoidf_(t0[j]); o[4 + j] = a1[j] * sigmoidf_(t1[j]); }
;         u32x4 w; w.x = pk(o[0], o[1]); w.y = pk(o[2], o[3]); w.z = pk(o[4], o[5]); w.w = pk(o[6], o[7]);
;         gst<u32x4>(g.o0 + (size_t)row * 1024 + ca, w);
	v_fma_f32 v148, -v148, v186, v167
	v_div_fmas_f32 v148, v148, v165, v186
	v_div_fixup_f32 v182, v148, v182, 1.0
	v_pk_mul_f32 v[182:183], v[184:185], v[182:183]
	s_nop 0
	v_cvt_pk_bf16_f32 v179, v182, v183
	global_store_dwordx4 v[174:175], v[176:179], off
	s_nop 1
	v_mov_b32_e32 v148, v239
	v_or_b32_e32 v174, 48, v166
	v_ashrrev_i32_e32 v175, 31, v174
	v_lshlrev_b64 v[174:175], 11, v[174:175]
	v_lshl_add_u64 v[174:175], s[64:65], 0, v[174:175]
	v_lshl_add_u64 v[172:173], v[174:175], 0, v[172:173]
	v_fma_f32 v165, v36, v148, v140
	v_mul_f32_e32 v165, 0xbfb8aa3b, v165
	v_exp_f32_e32 v176, v165
	v_fma_f32 v165, v32, v148, v132
	v_mul_f32_e32 v165, 0xbfb8aa3b, v165
	v_exp_f32_e32 v178, v165
	v_fma_f32 v165, v37, v148, v141
	v_mul_f32_e32 v165, 0xbfb8aa3b, v165
	v_exp_f32_e32 v177, v165
	v_pk_fma_f32 v[180:181], v[100:101], v[148:149], v[136:137] op_sel_hi:[1,0,1]
	v_pk_add_f32 v[176:177], v[176:177], 1.0 op_sel_hi:[1,0]
	s_nop 0
	v_div_scale_f32 v165, s[26:27], v177, v177, 1.0
	v_rcp_f32_e32 v167, v165
	s_nop 0
	v_fma_f32 v179, -v165, v167, 1.0
	v_fmac_f32_e32 v167, v179, v167
	v_div_scale_f32 v179, vcc, 1.0, v177, 1.0
	v_mul_f32_e32 v182, v179, v167
	v_fma_f32 v183, -v165, v182, v179
	v_fmac_f32_e32 v182, v183, v167
	v_fma_f32 v165, -v165, v182, v179
	v_div_fmas_f32 v165, v165, v167, v182
	v_div_fixup_f32 v177, v165, v177, 1.0
	v_div_scale_f32 v165, s[26:27], v176, v176, 1.0
	v_rcp_f32_e32 v167, v165
	s_nop 0
	v_fma_f32 v179, -v165, v167, 1.0
	v_fmac_f32_e32 v167, v179, v167
	v_div_scale_f32 v179, vcc, 1.0, v176, 1.0
	v_mul_f32_e32 v182, v179, v167
	v_fma_f32 v183, -v165, v182, v179
	v_fmac_f32_e32 v182, v183, v167
	v_fma_f32 v165, -v165, v182, v179
	v_div_fmas_f32 v165, v165, v167, v182
	v_div_fixup_f32 v176, v165, v176, 1.0
	v_fma_f32 v165, v33, v148, v133
	v_mul_f32_e32 v165, 0xbfb8aa3b, v165
	v_exp_f32_e32 v179, v165
	v_pk_mul_f32 v[176:177], v[180:181], v[176:177]
	v_pk_fma_f32 v[180:181], v[96:97], v[148:149], v[128:129] op_sel_hi:[1,0,1]
	v_cvt_pk_bf16_f32 v176, v176, v177
	v_pk_add_f32 v[178:179], v[178:179], 1.0 op_sel_hi:[1,0]
	s_nop 0
	v_div_scale_f32 v165, s[26:27], v179, v179, 1.0
	v_rcp_f32_e32 v167, v165
	s_nop 0
	v_fma_f32 v182, -v165, v167, 1.0
	v_fmac_f32_e32 v167, v182, v167
	v_div_scale_f32 v182, vcc, 1.0, v179, 1.0
	v_mul_f32_e32 v183, v182, v167
	v_fma_f32 v184, -v165, v183, v182
	v_fmac_f32_e32 v183, v184, v167
	v_fma_f32 v165, -v165, v183, v182
	v_div_fmas_f32 v165, v165, v167, v183
	v_div_fixup_f32 v179, v165, v179, 1.0
	v_div_scale_f32 v165, s[26:27], v178, v178, 1.0
	v_rcp_f32_e32 v167, v165
	s_nop 0
	v_fma_f32 v182, -v165, v167, 1.0
	v_fmac_f32_e32 v167, v182, v167
	v_div_scale_f32 v182, vcc, 1.0, v178, 1.0
	v_mul_f32_e32 v183, v182, v167
	v_fma_f32 v184, -v165, v183, v182
	v_fmac_f32_e32 v183, v184, v167
	v_fma_f32 v165, -v165, v183, v182
	v_div_fmas_f32 v165, v165, v167, v183
	v_div_fixup_f32 v178, v165, v178, 1.0
	v_fma_f32 v165, v38, v148, v142
	v_mul_f32_e32 v165, 0xbfb8aa3b, v165
	v_pk_mul_f32 v[178:179], v[180:181], v[178:179]
	v_exp_f32_e32 v180, v165
	v_fma_f32 v165, v34, v148, v134
	v_mul_f32_e32 v165, 0xbfb8aa3b, v165
	v_exp_f32_e32 v182, v165
	v_fma_f32 v165, v39, v148, v143
	v_mul_f32_e32 v165, 0xbfb8aa3b, v165
	v_exp_f32_e32 v181, v165
	v_pk_fma_f32 v[184:185], v[102:103], v[148:149], v[138:139] op_sel_hi:[1,0,1]
	v_cvt_pk_bf16_f32 v178, v178, v179
	v_pk_add_f32 v[180:181], v[180:181], 1.0 op_sel_hi:[1,0]
	s_nop 0
	v_div_scale_f32 v165, s[26:27], v181, v181, 1.0
	v_rcp_f32_e32 v167, v165
	s_nop 0
	v_fma_f32 v183, -v165, v167, 1.0
	v_fmac_f32_e32 v167, v183, v167
	v_div_scale_f32 v183, vcc, 1.0, v181, 1.0
	v_mul_f32_e32 v186, v183, v167
	v_fma_f32 v187, -v165, v186, v183
	v_fmac_f32_e32 v186, v187, v167
	v_fma_f32 v165, -v165, v186, v183
	v_div_fmas_f32 v165, v165, v167, v186
	v_div_fixup_f32 v181, v165, v181, 1.0
	v_div_scale_f32 v165, s[26:27], v180, v180, 1.0
	v_rcp_f32_e32 v167, v165
	s_nop 0
	v_fma_f32 v183, -v165, v167, 1.0
	v_fmac_f32_e32 v167, v183, v167
	v_div_scale_f32 v183, vcc, 1.0, v180, 1.0
	v_mul_f32_e32 v186, v183, v167
	v_fma_f32 v187, -v165, v186, v183
	v_fmac_f32_e32 v186, v187, v167
	v_fma_f32 v165, -v165, v186, v183
	v_div_fmas_f32 v165, v165, v167, v186
	v_div_fixup_f32 v180, v165, v180, 1.0
	v_fma_f32 v165, v35, v148, v135
	v_mul_f32_e32 v165, 0xbfb8aa3b, v165
	v_exp_f32_e32 v183, v165
	v_pk_mul_f32 v[180:181], v[184:185], v[180:181]
	v_pk_fma_f32 v[184:185], v[98:99], v[148:149], v[130:131] op_sel_hi:[1,0,1]
	v_cvt_pk_bf16_f32 v177, v180, v181
	v_pk_add_f32 v[182:183], v[182:183], 1.0 op_sel_hi:[1,0]
	s_nop 0
	v_div_scale_f32 v148, s[26:27], v183, v183, 1.0
	v_rcp_f32_e32 v165, v148
	s_nop 0
	v_fma_f32 v167, -v148, v165, 1.0
	v_fmac_f32_e32 v165, v167, v165
	v_div_scale_f32 v167, vcc, 1.0, v183, 1.0
	v_mul_f32_e32 v186, v167, v165
	v_fma_f32 v187, -v148, v186, v167
	v_fmac_f32_e32 v186, v187, v165
	v_fma_f32 v148, -v148, v186, v167
	v_div_fmas_f32 v148, v148, v165, v186
	v_div_fixup_f32 v183, v148, v183, 1.0
	v_div_scale_f32 v148, s[26:27], v182, v182, 1.0
	v_rcp_f32_e32 v165, v148
	s_nop 0
	v_fma_f32 v167, -v148, v165, 1.0
	v_fmac_f32_e32 v165, v167, v165
	v_div_scale_f32 v167, vcc, 1.0, v182, 1.0
	v_mul_f32_e32 v186, v167, v165
	v_fma_f32 v187, -v148, v186, v167
	v_fmac_f32_e32 v186, v187, v165
	v_fma_f32 v148, -v148, v186, v167
	v_div_fmas_f32 v148, v148, v165, v186
	v_div_fixup_f32 v182, v148, v182, 1.0
	v_pk_mul_f32 v[182:183], v[184:185], v[182:183]
	s_nop 0
	v_cvt_pk_bf16_f32 v179, v182, v183
	global_store_dwordx4 v[172:173], v[176:179], off
	s_nop 1
	v_mov_b32_e32 v148, v240
	v_fma_f32 v165, v28, v148, v140
	v_mul_f32_e32 v165, 0xbfb8aa3b, v165
	v_exp_f32_e32 v172, v165
; DI unsigned pk(float lo, float hi) { f32x2 v = {lo, hi}; bf2_t b = __builtin_convertvector(v, bf2_t); return __builtin_bit_cast(unsigned, b); }
; DI float sigmoidf_(float x) { return 1.0f / (1.0f + __expf(-x)); }
; DI void gemm_epilogue(const GemmDesc& g, f32x4 (&acc)[2][2][4][2], int brow, int bcol, int wr, int wc, int fr, int fq) {
;     ...
;     for (int ai = 0; ai < 2; ++ai)
; #pragma unroll
;       for (int m = 0; m < 4; ++m) {
;         const int row = rowb + ai * HALF + m * 16;
;         const float ru = gld<float>(g.rowscale + row);
;         const f32x4 a0 = acc[ai][0][m][0] * ru + ba0, a1 = acc[ai][0][m][1] * ru + ba1, t0 = acc[ai][1][m][0] * ru + bg0, t1 = acc[ai][1][m][1] * ru + bg1;
;         float o[8];
; #pragma unroll
;         for (int j = 0; j < 4; ++j) { o[j] = a0[j] * sigmoidf_(t0[j]); o[4 + j] = a1[j] * sigmoidf_(t1[j]); }
;         u32x4 w; w.x = pk(o[0], o[1]); w.y = pk(o[2], o[3]); w.z = pk(o[4], o[5]); w.w = pk(o[6], o[7]);
;         gst<u32x4>(g.o0 + (size_t)row * 1024 + ca, w);
	v_fma_f32 v165, v24, v148, v132
	v_mul_f32_e32 v165, 0xbfb8aa3b, v165
	v_exp_f32_e32 v174, v165
	v_fma_f32 v165, v29, v148, v141
	v_mul_f32_e32 v165, 0xbfb8aa3b, v165
	v_exp_f32_e32 v173, v165
	v_pk_fma_f32 v[176:177], v[92:93], v[148:149], v[136:137] op_sel_hi:[1,0,1]
	v_pk_add_f32 v[172:173], v[172:173], 1.0 op_sel_hi:[1,0]
	s_nop 0
	v_div_scale_f32 v165, s[26:27], v173, v173, 1.0
	v_rcp_f32_e32 v167, v165
	s_nop 0
	v_fma_f32 v175, -v165, v167, 1.0
	v_fmac_f32_e32 v167, v175, v167
	v_div_scale_f32 v175, vcc, 1.0, v173, 1.0
	v_mul_f32_e32 v178, v175, v167
	v_fma_f32 v179, -v165, v178, v175
	v_fmac_f32_e32 v178, v179, v167
	v_fma_f32 v165, -v165, v178, v175
	v_div_fmas_f32 v165, v165, v167, v178
	v_div_fixup_f32 v173, v165, v173, 1.0
	v_div_scale_f32 v165, s[26:27], v172, v172, 1.0
	v_rcp_f32_e32 v167, v165
	s_nop 0
	v_fma_f32 v175, -v165, v167, 1.0
	v_fmac_f32_e32 v167, v175, v167
	v_div_scale_f32 v175, vcc, 1.0, v172, 1.0
	v_mul_f32_e32 v178, v175, v167
	v_fma_f32 v179, -v165, v178, v175
	v_fmac_f32_e32 v178, v179, v167
	v_fma_f32 v165, -v165, v178, v175
	v_div_fmas_f32 v165, v165, v167, v178
	v_div_fixup_f32 v172, v165, v172, 1.0
	v_fma_f32 v165, v25, v148, v133
	v_mul_f32_e32 v165, 0xbfb8aa3b, v165
	v_exp_f32_e32 v175, v165
	v_pk_mul_f32 v[172:173], v[176:177], v[172:173]
	v_pk_fma_f32 v[176:177], v[88:89], v[148:149], v[128:129] op_sel_hi:[1,0,1]
	v_cvt_pk_bf16_f32 v172, v172, v173
	v_pk_add_f32 v[174:175], v[174:175], 1.0 op_sel_hi:[1,0]
	s_nop 0
	v_div_scale_f32 v165, s[26:27], v175, v175, 1.0
	v_rcp_f32_e32 v167, v165
	s_nop 0
	v_fma_f32 v178, -v165, v167, 1.0
	v_fmac_f32_e32 v167, v178, v167
	v_div_scale_f32 v178, vcc, 1.0, v175, 1.0
	v_mul_f32_e32 v179, v178, v167
	v_fma_f32 v180, -v165, v179, v178
	v_fmac_f32_e32 v179, v180, v167
	v_fma_f32 v165, -v165, v179, v178
	v_div_fmas_f32 v165, v165, v167, v179
	v_div_fixup_f32 v175, v165, v175, 1.0
	v_div_scale_f32 v165, s[26:27], v174, v174, 1.0
	v_rcp_f32_e32 v167, v165
	s_nop 0
	v_fma_f32 v178, -v165, v167, 1.0
	v_fmac_f32_e32 v167, v178, v167
	v_div_scale_f32 v178, vcc, 1.0, v174, 1.0
	v_mul_f32_e32 v179, v178, v167
	v_fma_f32 v180, -v165, v179, v178
	v_fmac_f32_e32 v179, v180, v167
	v_fma_f32 v165, -v165, v179, v178
	v_div_fmas_f32 v165, v165, v167, v179
	v_div_fixup_f32 v174, v165, v174, 1.0
	v_fma_f32 v165, v30, v148, v142
	v_mul_f32_e32 v165, 0xbfb8aa3b, v165
	v_pk_mul_f32 v[174:175], v[176:177], v[174:175]
	v_exp_f32_e32 v176, v165
	v_fma_f32 v165, v26, v148, v134
	v_mul_f32_e32 v165, 0xbfb8aa3b, v165
	v_exp_f32_e32 v178, v165
	v_fma_f32 v165, v31, v148, v143
	v_mul_f32_e32 v165, 0xbfb8aa3b, v165
	v_exp_f32_e32 v177, v165
	v_pk_fma_f32 v[180:181], v[94:95], v[148:149], v[138:139] op_sel_hi:[1,0,1]
	v_cvt_pk_bf16_f32 v174, v174, v175
	v_pk_add_f32 v[176:177], v[176:177], 1.0 op_sel_hi:[1,0]
	s_nop 0
	v_div_scale_f32 v165, s[26:27], v177, v177, 1.0
	v_rcp_f32_e32 v167, v165
	s_nop 0
	v_fma_f32 v179, -v165, v167, 1.0
	v_fmac_f32_e32 v167, v179, v167
	v_div_scale_f32 v179, vcc, 1.0, v177, 1.0
	v_mul_f32_e32 v182, v179, v167
	v_fma_f32 v183, -v165, v182, v179
	v_fmac_f32_e32 v182, v183, v167
	v_fma_f32 v165, -v165, v182, v179
	v_div_fmas_f32 v165, v165, v167, v182
	v_div_fixup_f32 v177, v165, v177, 1.0
	v_div_scale_f32 v165, s[26:27], v176, v176, 1.0
	v_rcp_f32_e32 v167, v165
	s_nop 0
	v_fma_f32 v179, -v165, v167, 1.0
	v_fmac_f32_e32 v167, v179, v167
	v_div_scale_f32 v179, vcc, 1.0, v176, 1.0
	v_mul_f32_e32 v182, v179, v167
	v_fma_f32 v183, -v165, v182, v179
	v_fmac_f32_e32 v182, v183, v167
	v_fma_f32 v165, -v165, v182, v179
	v_div_fmas_f32 v165, v165, v167, v182
	v_div_fixup_f32 v176, v165, v176, 1.0
	v_fma_f32 v165, v27, v148, v135
	v_mul_f32_e32 v165, 0xbfb8aa3b, v165
	v_exp_f32_e32 v179, v165
	v_pk_mul_f32 v[176:177], v[180:181], v[176:177]
	v_pk_fma_f32 v[180:181], v[90:91], v[148:149], v[130:131] op_sel_hi:[1,0,1]
	v_cvt_pk_bf16_f32 v173, v176, v177
	v_pk_add_f32 v[178:179], v[178:179], 1.0 op_sel_hi:[1,0]
	s_nop 0
	v_div_scale_f32 v148, s[26:27], v179, v179, 1.0
	v_rcp_f32_e32 v165, v148
	s_nop 0
	v_fma_f32 v167, -v148, v165, 1.0
	v_fmac_f32_e32 v165, v167, v165
	v_div_scale_f32 v167, vcc, 1.0, v179, 1.0
	v_mul_f32_e32 v182, v167, v165
	v_fma_f32 v183, -v148, v182, v167
	v_fmac_f32_e32 v182, v183, v165
	v_fma_f32 v148, -v148, v182, v167
	v_div_fmas_f32 v148, v148, v165, v182
	v_div_fixup_f32 v179, v148, v179, 1.0
	v_div_scale_f32 v148, s[26:27], v178, v178, 1.0
	v_rcp_f32_e32 v165, v148
	s_mov_b32 s26, 0x40000
	v_fma_f32 v167, -v148, v165, 1.0
	v_fmac_f32_e32 v165, v167, v165
	v_div_scale_f32 v167, vcc, 1.0, v178, 1.0
	v_mul_f32_e32 v182, v167, v165
	v_fma_f32 v183, -v148, v182, v167
	v_fmac_f32_e32 v182, v183, v165
	v_fma_f32 v148, -v148, v182, v167
	v_div_fmas_f32 v148, v148, v165, v182
	v_div_fixup_f32 v178, v148, v178, 1.0
	v_pk_mul_f32 v[178:179], v[180:181], v[178:179]
	v_add_co_u32_e32 v176, vcc, s26, v170
	v_cvt_pk_bf16_f32 v175, v178, v179
	s_nop 0
	v_addc_co_u32_e32 v177, vcc, 0, v171, vcc
	global_store_dwordx4 v[176:177], v[172:175], off
	s_nop 1
	v_mov_b32_e32 v148, v241
	v_fma_f32 v165, v20, v148, v140
	v_mul_f32_e32 v165, 0xbfb8aa3b, v165
	v_exp_f32_e32 v172, v165
	v_fma_f32 v165, v16, v148, v132
	v_mul_f32_e32 v165, 0xbfb8aa3b, v165
	v_exp_f32_e32 v174, v165
	v_fma_f32 v165, v21, v148, v141
	v_mul_f32_e32 v165, 0xbfb8aa3b, v165
	v_exp_f32_e32 v173, v165
	v_pk_fma_f32 v[176:177], v[84:85], v[148:149], v[136:137] op_sel_hi:[1,0,1]
	v_pk_add_f32 v[172:173], v[172:173], 1.0 op_sel_hi:[1,0]
	s_nop 0
	v_div_scale_f32 v165, s[26:27], v173, v173, 1.0
	v_rcp_f32_e32 v167, v165
	s_nop 0
	v_fma_f32 v175, -v165, v167, 1.0
	v_fmac_f32_e32 v167, v175, v167
; DI unsigned pk(float lo, float hi) { f32x2 v = {lo, hi}; bf2_t b = __builtin_convertvector(v, bf2_t); return __builtin_bit_cast(unsigned, b); }
; DI float sigmoidf_(float x) { return 1.0f / (1.0f + __expf(-x)); }
; DI void gemm_epilogue(const GemmDesc& g, f32x4 (&acc)[2][2][4][2], int brow, int bcol, int wr, int wc, int fr, int fq) {
;     ...
;     for (int ai = 0; ai < 2; ++ai)
; #pragma unroll
;       for (int m = 0; m < 4; ++m) {
;         const int row = rowb + ai * HALF + m * 16;
;         const float ru = gld<float>(g.rowscale + row);
;         const f32x4 a0 = acc[ai][0][m][0] * ru + ba0, a1 = acc[ai][0][m][1] * ru + ba1, t0 = acc[ai][1][m][0] * ru + bg0, t1 = acc[ai][1][m][1] * ru + bg1;
;         float o[8];
; #pragma unroll
;         for (int j = 0; j < 4; ++j) { o[j] = a0[j] * sigmoidf_(t0[j]); o[4 + j] = a1[j] * sigmoidf_(t1[j]); }
;         u32x4 w; w.x = pk(o[0], o[1]); w.y = pk(o[2], o[3]); w.z = pk(o[4], o[5]); w.w = pk(o[6], o[7]);
;         gst<u32x4>(g.o0 + (size_t)row * 1024 + ca, w);
	v_div_scale_f32 v175, vcc, 1.0, v173, 1.0
	v_mul_f32_e32 v178, v175, v167
	v_fma_f32 v179, -v165, v178, v175
	v_fmac_f32_e32 v178, v179, v167
	v_fma_f32 v165, -v165, v178, v175
	v_div_fmas_f32 v165, v165, v167, v178
	v_div_fixup_f32 v173, v165, v173, 1.0
	v_div_scale_f32 v165, s[26:27], v172, v172, 1.0
	v_rcp_f32_e32 v167, v165
	s_nop 0
	v_fma_f32 v175, -v165, v167, 1.0
	v_fmac_f32_e32 v167, v175, v167
	v_div_scale_f32 v175, vcc, 1.0, v172, 1.0
	v_mul_f32_e32 v178, v175, v167
	v_fma_f32 v179, -v165, v178, v175
	v_fmac_f32_e32 v178, v179, v167
	v_fma_f32 v165, -v165, v178, v175
	v_div_fmas_f32 v165, v165, v167, v178
	v_div_fixup_f32 v172, v165, v172, 1.0
	v_fma_f32 v165, v17, v148, v133
	v_mul_f32_e32 v165, 0xbfb8aa3b, v165
	v_exp_f32_e32 v175, v165
	v_pk_mul_f32 v[172:173], v[176:177], v[172:173]
	v_pk_fma_f32 v[176:177], v[80:81], v[148:149], v[128:129] op_sel_hi:[1,0,1]
	v_cvt_pk_bf16_f32 v172, v172, v173
	v_pk_add_f32 v[174:175], v[174:175], 1.0 op_sel_hi:[1,0]
	s_nop 0
	v_div_scale_f32 v165, s[26:27], v175, v175, 1.0
	v_rcp_f32_e32 v167, v165
	s_nop 0
	v_fma_f32 v178, -v165, v167, 1.0
	v_fmac_f32_e32 v167, v178, v167
	v_div_scale_f32 v178, vcc, 1.0, v175, 1.0
	v_mul_f32_e32 v179, v178, v167
	v_fma_f32 v180, -v165, v179, v178
	v_fmac_f32_e32 v179, v180, v167
	v_fma_f32 v165, -v165, v179, v178
	v_div_fmas_f32 v165, v165, v167, v179
	v_div_fixup_f32 v175, v165, v175, 1.0
	v_div_scale_f32 v165, s[26:27], v174, v174, 1.0
	v_rcp_f32_e32 v167, v165
	s_nop 0
	v_fma_f32 v178, -v165, v167, 1.0
	v_fmac_f32_e32 v167, v178, v167
	v_div_scale_f32 v178, vcc, 1.0, v174, 1.0
	v_mul_f32_e32 v179, v178, v167
	v_fma_f32 v180, -v165, v179, v178
	v_fmac_f32_e32 v179, v180, v167
	v_fma_f32 v165, -v165, v179, v178
	v_div_fmas_f32 v165, v165, v167, v179
	v_div_fixup_f32 v174, v165, v174, 1.0
	v_fma_f32 v165, v22, v148, v142
	v_mul_f32_e32 v165, 0xbfb8aa3b, v165
	v_pk_mul_f32 v[174:175], v[176:177], v[174:175]
	v_exp_f32_e32 v176, v165
	v_fma_f32 v165, v18, v148, v134
	v_mul_f32_e32 v165, 0xbfb8aa3b, v165
	v_exp_f32_e32 v178, v165
	v_fma_f32 v165, v23, v148, v143
	v_mul_f32_e32 v165, 0xbfb8aa3b, v165
	v_exp_f32_e32 v177, v165
	v_pk_fma_f32 v[180:181], v[86:87], v[148:149], v[138:139] op_sel_hi:[1,0,1]
	v_cvt_pk_bf16_f32 v174, v174, v175
	v_pk_add_f32 v[176:177], v[176:177], 1.0 op_sel_hi:[1,0]
	s_nop 0
	v_div_scale_f32 v165, s[26:27], v177, v177, 1.0
	v_rcp_f32_e32 v167, v165
	s_nop 0
	v_fma_f32 v179, -v165, v167, 1.0
	v_fmac_f32_e32 v167, v179, v167
	v_div_scale_f32 v179, vcc, 1.0, v177, 1.0
	v_mul_f32_e32 v182, v179, v167
	v_fma_f32 v183, -v165, v182, v179
	v_fmac_f32_e32 v182, v183, v167
	v_fma_f32 v165, -v165, v182, v179
	v_div_fmas_f32 v165, v165, v167, v182
	v_div_fixup_f32 v177, v165, v177, 1.0
	v_div_scale_f32 v165, s[26:27], v176, v176, 1.0
	v_rcp_f32_e32 v167, v165
	s_nop 0
	v_fma_f32 v179, -v165, v167, 1.0
	v_fmac_f32_e32 v167, v179, v167
	v_div_scale_f32 v179, vcc, 1.0, v176, 1.0
	v_mul_f32_e32 v182, v179, v167
	v_fma_f32 v183, -v165, v182, v179
	v_fmac_f32_e32 v182, v183, v167
	v_fma_f32 v165, -v165, v182, v179
	v_div_fmas_f32 v165, v165, v167, v182
	v_div_fixup_f32 v176, v165, v176, 1.0
	v_fma_f32 v165, v19, v148, v135
	v_mul_f32_e32 v165, 0xbfb8aa3b, v165
	v_exp_f32_e32 v179, v165
	v_pk_mul_f32 v[176:177], v[180:181], v[176:177]
	v_pk_fma_f32 v[180:181], v[82:83], v[148:149], v[130:131] op_sel_hi:[1,0,1]
	v_cvt_pk_bf16_f32 v173, v176, v177
	v_pk_add_f32 v[178:179], v[178:179], 1.0 op_sel_hi:[1,0]
	s_nop 0
	v_div_scale_f32 v148, s[26:27], v179, v179, 1.0
	v_rcp_f32_e32 v165, v148
	s_nop 0
	v_fma_f32 v167, -v148, v165, 1.0
	v_fmac_f32_e32 v165, v167, v165
	v_div_scale_f32 v167, vcc, 1.0, v179, 1.0
	v_mul_f32_e32 v182, v167, v165
	v_fma_f32 v183, -v148, v182, v167
	v_fmac_f32_e32 v182, v183, v165
	v_fma_f32 v148, -v148, v182, v167
	v_div_fmas_f32 v148, v148, v165, v182
	v_div_fixup_f32 v179, v148, v179, 1.0
	v_div_scale_f32 v148, s[26:27], v178, v178, 1.0
	v_rcp_f32_e32 v165, v148
	s_mov_b32 s26, 0x48000
	v_fma_f32 v167, -v148, v165, 1.0
	v_fmac_f32_e32 v165, v167, v165
	v_div_scale_f32 v167, vcc, 1.0, v178, 1.0
	v_mul_f32_e32 v182, v167, v165
	v_fma_f32 v183, -v148, v182, v167
	v_fmac_f32_e32 v182, v183, v165
	v_fma_f32 v148, -v148, v182, v167
	v_div_fmas_f32 v148, v148, v165, v182
	v_div_fixup_f32 v178, v148, v178, 1.0
	v_pk_mul_f32 v[178:179], v[180:181], v[178:179]
	v_add_co_u32_e32 v176, vcc, s26, v170
	v_cvt_pk_bf16_f32 v175, v178, v179
	s_nop 0
	v_addc_co_u32_e32 v177, vcc, 0, v171, vcc
	global_store_dwordx4 v[176:177], v[172:175], off
	s_nop 1
	v_mov_b32_e32 v148, v242
	v_fma_f32 v165, v12, v148, v140
	v_mul_f32_e32 v165, 0xbfb8aa3b, v165
	v_exp_f32_e32 v172, v165
	v_fma_f32 v165, v8, v148, v132
	v_mul_f32_e32 v165, 0xbfb8aa3b, v165
	v_exp_f32_e32 v174, v165
	v_fma_f32 v165, v13, v148, v141
	v_mul_f32_e32 v165, 0xbfb8aa3b, v165
	v_exp_f32_e32 v173, v165
	v_pk_fma_f32 v[176:177], v[76:77], v[148:149], v[136:137] op_sel_hi:[1,0,1]
	v_pk_add_f32 v[172:173], v[172:173], 1.0 op_sel_hi:[1,0]
	s_nop 0
	v_div_scale_f32 v165, s[26:27], v173, v173, 1.0
	v_rcp_f32_e32 v167, v165
	s_nop 0
	v_fma_f32 v175, -v165, v167, 1.0
	v_fmac_f32_e32 v167, v175, v167
	v_div_scale_f32 v175, vcc, 1.0, v173, 1.0
	v_mul_f32_e32 v178, v175, v167
	v_fma_f32 v179, -v165, v178, v175
	v_fmac_f32_e32 v178, v179, v167
	v_fma_f32 v165, -v165, v178, v175
	v_div_fmas_f32 v165, v165, v167, v178
	v_div_fixup_f32 v173, v165, v173, 1.0
	v_div_scale_f32 v165, s[26:27], v172, v172, 1.0
	v_rcp_f32_e32 v167, v165
	s_nop 0
	v_fma_f32 v175, -v165, v167, 1.0
	v_fmac_f32_e32 v167, v175, v167
	v_div_scale_f32 v175, vcc, 1.0, v172, 1.0
	v_mul_f32_e32 v178, v175, v167
	v_fma_f32 v179, -v165, v178, v175
; DI unsigned pk(float lo, float hi) { f32x2 v = {lo, hi}; bf2_t b = __builtin_convertvector(v, bf2_t); return __builtin_bit_cast(unsigned, b); }
; DI float sigmoidf_(float x) { return 1.0f / (1.0f + __expf(-x)); }
; DI void gemm_epilogue(const GemmDesc& g, f32x4 (&acc)[2][2][4][2], int brow, int bcol, int wr, int wc, int fr, int fq) {
;     ...
;         const int row = rowb + ai * HALF + m * 16;
;         const float ru = gld<float>(g.rowscale + row);
;         const f32x4 a0 = acc[ai][0][m][0] * ru + ba0, a1 = acc[ai][0][m][1] * ru + ba1, t0 = acc[ai][1][m][0] * ru + bg0, t1 = acc[ai][1][m][1] * ru + bg1;
;         float o[8];
; #pragma unroll
;         for (int j = 0; j < 4; ++j) { o[j] = a0[j] * sigmoidf_(t0[j]); o[4 + j] = a1[j] * sigmoidf_(t1[j]); }
;         u32x4 w; w.x = pk(o[0], o[1]); w.y = pk(o[2], o[3]); w.z = pk(o[4], o[5]); w.w = pk(o[6], o[7]);
;         gst<u32x4>(g.o0 + (size_t)row * 1024 + ca, w);
	v_fmac_f32_e32 v178, v179, v167
	v_fma_f32 v165, -v165, v178, v175
	v_div_fmas_f32 v165, v165, v167, v178
	v_div_fixup_f32 v172, v165, v172, 1.0
	v_fma_f32 v165, v9, v148, v133
	v_mul_f32_e32 v165, 0xbfb8aa3b, v165
	v_exp_f32_e32 v175, v165
	v_pk_mul_f32 v[172:173], v[176:177], v[172:173]
	v_pk_fma_f32 v[176:177], v[72:73], v[148:149], v[128:129] op_sel_hi:[1,0,1]
	v_cvt_pk_bf16_f32 v172, v172, v173
	v_pk_add_f32 v[174:175], v[174:175], 1.0 op_sel_hi:[1,0]
	s_nop 0
	v_div_scale_f32 v165, s[26:27], v175, v175, 1.0
	v_rcp_f32_e32 v167, v165
	s_nop 0
	v_fma_f32 v178, -v165, v167, 1.0
	v_fmac_f32_e32 v167, v178, v167
	v_div_scale_f32 v178, vcc, 1.0, v175, 1.0
	v_mul_f32_e32 v179, v178, v167
	v_fma_f32 v180, -v165, v179, v178
	v_fmac_f32_e32 v179, v180, v167
	v_fma_f32 v165, -v165, v179, v178
	v_div_fmas_f32 v165, v165, v167, v179
	v_div_fixup_f32 v175, v165, v175, 1.0
	v_div_scale_f32 v165, s[26:27], v174, v174, 1.0
	v_rcp_f32_e32 v167, v165
	s_nop 0
	v_fma_f32 v178, -v165, v167, 1.0
	v_fmac_f32_e32 v167, v178, v167
	v_div_scale_f32 v178, vcc, 1.0, v174, 1.0
	v_mul_f32_e32 v179, v178, v167
	v_fma_f32 v180, -v165, v179, v178
	v_fmac_f32_e32 v179, v180, v167
	v_fma_f32 v165, -v165, v179, v178
	v_div_fmas_f32 v165, v165, v167, v179
	v_div_fixup_f32 v174, v165, v174, 1.0
	v_fma_f32 v165, v14, v148, v142
	v_mul_f32_e32 v165, 0xbfb8aa3b, v165
	v_pk_mul_f32 v[174:175], v[176:177], v[174:175]
	v_exp_f32_e32 v176, v165
	v_fma_f32 v165, v10, v148, v134
	v_mul_f32_e32 v165, 0xbfb8aa3b, v165
	v_exp_f32_e32 v178, v165
	v_fma_f32 v165, v15, v148, v143
	v_mul_f32_e32 v165, 0xbfb8aa3b, v165
	v_exp_f32_e32 v177, v165
	v_pk_fma_f32 v[180:181], v[78:79], v[148:149], v[138:139] op_sel_hi:[1,0,1]
	v_cvt_pk_bf16_f32 v174, v174, v175
	v_pk_add_f32 v[176:177], v[176:177], 1.0 op_sel_hi:[1,0]
	s_nop 0
	v_div_scale_f32 v165, s[26:27], v177, v177, 1.0
	v_rcp_f32_e32 v167, v165
	s_nop 0
	v_fma_f32 v179, -v165, v167, 1.0
	v_fmac_f32_e32 v167, v179, v167
	v_div_scale_f32 v179, vcc, 1.0, v177, 1.0
	v_mul_f32_e32 v182, v179, v167
	v_fma_f32 v183, -v165, v182, v179
	v_fmac_f32_e32 v182, v183, v167
	v_fma_f32 v165, -v165, v182, v179
	v_div_fmas_f32 v165, v165, v167, v182
	v_div_fixup_f32 v177, v165, v177, 1.0
	v_div_scale_f32 v165, s[26:27], v176, v176, 1.0
	v_rcp_f32_e32 v167, v165
	s_nop 0
	v_fma_f32 v179, -v165, v167, 1.0
	v_fmac_f32_e32 v167, v179, v167
	v_div_scale_f32 v179, vcc, 1.0, v176, 1.0
	v_mul_f32_e32 v182, v179, v167
	v_fma_f32 v183, -v165, v182, v179
	v_fmac_f32_e32 v182, v183, v167
	v_fma_f32 v165, -v165, v182, v179
	v_div_fmas_f32 v165, v165, v167, v182
	v_div_fixup_f32 v176, v165, v176, 1.0
	v_fma_f32 v165, v11, v148, v135
	v_mul_f32_e32 v165, 0xbfb8aa3b, v165
	v_exp_f32_e32 v179, v165
	v_pk_mul_f32 v[176:177], v[180:181], v[176:177]
	v_pk_fma_f32 v[180:181], v[74:75], v[148:149], v[130:131] op_sel_hi:[1,0,1]
	v_cvt_pk_bf16_f32 v173, v176, v177
	v_pk_add_f32 v[178:179], v[178:179], 1.0 op_sel_hi:[1,0]
	s_nop 0
	v_div_scale_f32 v148, s[26:27], v179, v179, 1.0
	v_rcp_f32_e32 v165, v148
	s_nop 0
	v_fma_f32 v167, -v148, v165, 1.0
	v_fmac_f32_e32 v165, v167, v165
	v_div_scale_f32 v167, vcc, 1.0, v179, 1.0
	v_mul_f32_e32 v182, v167, v165
	v_fma_f32 v183, -v148, v182, v167
	v_fmac_f32_e32 v182, v183, v165
	v_fma_f32 v148, -v148, v182, v167
	v_div_fmas_f32 v148, v148, v165, v182
	v_div_fixup_f32 v179, v148, v179, 1.0
	v_div_scale_f32 v148, s[26:27], v178, v178, 1.0
	v_rcp_f32_e32 v165, v148
	s_mov_b32 s26, 0x50000
	v_fma_f32 v167, -v148, v165, 1.0
	v_fmac_f32_e32 v165, v167, v165
	v_div_scale_f32 v167, vcc, 1.0, v178, 1.0
	v_mul_f32_e32 v182, v167, v165
	v_fma_f32 v183, -v148, v182, v167
	v_fmac_f32_e32 v182, v183, v165
	v_fma_f32 v148, -v148, v182, v167
	v_div_fmas_f32 v148, v148, v165, v182
	v_div_fixup_f32 v178, v148, v178, 1.0
	v_pk_mul_f32 v[178:179], v[180:181], v[178:179]
	v_add_co_u32_e32 v176, vcc, s26, v170
	v_cvt_pk_bf16_f32 v175, v178, v179
	s_nop 0
	v_addc_co_u32_e32 v177, vcc, 0, v171, vcc
	global_store_dwordx4 v[176:177], v[172:175], off
	s_nop 1
	v_mov_b32_e32 v148, v243
	v_fma_f32 v140, v4, v148, v140
	v_fma_f32 v141, v5, v148, v141
	v_mul_f32_e32 v140, 0xbfb8aa3b, v140
	v_mul_f32_e32 v141, 0xbfb8aa3b, v141
	v_exp_f32_e32 v140, v140
	v_exp_f32_e32 v141, v141
	v_fma_f32 v132, v0, v148, v132
	v_fma_f32 v133, v1, v148, v133
	v_mul_f32_e32 v132, 0xbfb8aa3b, v132
	v_pk_add_f32 v[140:141], v[140:141], 1.0 op_sel_hi:[1,0]
	v_mul_f32_e32 v133, 0xbfb8aa3b, v133
	v_div_scale_f32 v165, s[26:27], v141, v141, 1.0
	v_rcp_f32_e32 v167, v165
	v_exp_f32_e32 v132, v132
; DI unsigned pk(float lo, float hi) { f32x2 v = {lo, hi}; bf2_t b = __builtin_convertvector(v, bf2_t); return __builtin_bit_cast(unsigned, b); }
; DI float sigmoidf_(float x) { return 1.0f / (1.0f + __expf(-x)); }
; DI void gemm_epilogue(const GemmDesc& g, f32x4 (&acc)[2][2][4][2], int brow, int bcol, int wr, int wc, int fr, int fq) {
;     ...
;         const int row = rowb + ai * HALF + m * 16;
;         const float ru = gld<float>(g.rowscale + row);
;         const f32x4 a0 = acc[ai][0][m][0] * ru + ba0, a1 = acc[ai][0][m][1] * ru + ba1, t0 = acc[ai][1][m][0] * ru + bg0, t1 = acc[ai][1][m][1] * ru + bg1;
;         float o[8];
; #pragma unroll
;         for (int j = 0; j < 4; ++j) { o[j] = a0[j] * sigmoidf_(t0[j]); o[4 + j] = a1[j] * sigmoidf_(t1[j]); }
;         u32x4 w; w.x = pk(o[0], o[1]); w.y = pk(o[2], o[3]); w.z = pk(o[4], o[5]); w.w = pk(o[6], o[7]);
;         gst<u32x4>(g.o0 + (size_t)row * 1024 + ca, w);
	v_exp_f32_e32 v133, v133
	v_pk_fma_f32 v[136:137], v[68:69], v[148:149], v[136:137] op_sel_hi:[1,0,1]
	v_fma_f32 v168, -v165, v167, 1.0
	v_fmac_f32_e32 v167, v168, v167
	v_div_scale_f32 v168, vcc, 1.0, v141, 1.0
	v_mul_f32_e32 v169, v168, v167
	v_fma_f32 v172, -v165, v169, v168
	v_fmac_f32_e32 v169, v172, v167
	v_fma_f32 v165, -v165, v169, v168
	v_div_fmas_f32 v165, v165, v167, v169
	v_div_fixup_f32 v141, v165, v141, 1.0
	v_div_scale_f32 v165, s[26:27], v140, v140, 1.0
	v_rcp_f32_e32 v167, v165
	v_pk_add_f32 v[132:133], v[132:133], 1.0 op_sel_hi:[1,0]
	v_pk_fma_f32 v[128:129], v[64:65], v[148:149], v[128:129] op_sel_hi:[1,0,1]
	v_fmac_f32_e32 v143, v7, v148
	v_fma_f32 v168, -v165, v167, 1.0
	v_fmac_f32_e32 v167, v168, v167
	v_div_scale_f32 v168, vcc, 1.0, v140, 1.0
	v_mul_f32_e32 v169, v168, v167
	v_fma_f32 v172, -v165, v169, v168
	v_fmac_f32_e32 v169, v172, v167
	v_fma_f32 v165, -v165, v169, v168
	v_div_fmas_f32 v165, v165, v167, v169
	v_div_fixup_f32 v140, v165, v140, 1.0
	v_pk_mul_f32 v[136:137], v[136:137], v[140:141]
	v_div_scale_f32 v140, s[26:27], v133, v133, 1.0
	v_rcp_f32_e32 v141, v140
	v_pk_fma_f32 v[138:139], v[70:71], v[148:149], v[138:139] op_sel_hi:[1,0,1]
	v_fmac_f32_e32 v135, v3, v148
	v_fma_f32 v165, -v140, v141, 1.0
	v_fmac_f32_e32 v141, v165, v141
	v_div_scale_f32 v165, vcc, 1.0, v133, 1.0
	v_mul_f32_e32 v167, v165, v141
	v_fma_f32 v168, -v140, v167, v165
	v_fmac_f32_e32 v167, v168, v141
	v_fma_f32 v140, -v140, v167, v165
	v_div_fmas_f32 v140, v140, v141, v167
	v_div_fixup_f32 v133, v140, v133, 1.0
	v_div_scale_f32 v140, s[26:27], v132, v132, 1.0
	v_rcp_f32_e32 v141, v140
	s_nop 0
	v_fma_f32 v165, -v140, v141, 1.0
	v_fmac_f32_e32 v141, v165, v141
	v_div_scale_f32 v165, vcc, 1.0, v132, 1.0
	v_mul_f32_e32 v167, v165, v141
	v_fma_f32 v168, -v140, v167, v165
	v_fmac_f32_e32 v167, v168, v141
	v_fma_f32 v140, -v140, v167, v165
	v_div_fmas_f32 v140, v140, v141, v167
	v_div_fixup_f32 v132, v140, v132, 1.0
	v_pk_mul_f32 v[132:133], v[128:129], v[132:133]
	v_fma_f32 v129, v2, v148, v134
	v_fma_f32 v128, v6, v148, v142
	v_mul_f32_e32 v129, 0xbfb8aa3b, v129
	v_mul_f32_e32 v128, 0xbfb8aa3b, v128
	v_exp_f32_e32 v134, v129
	v_mul_f32_e32 v129, 0xbfb8aa3b, v143
	v_exp_f32_e32 v128, v128
	v_exp_f32_e32 v129, v129
	s_nop 0
	v_pk_add_f32 v[128:129], v[128:129], 1.0 op_sel_hi:[1,0]
	s_nop 0
	v_div_scale_f32 v140, s[26:27], v129, v129, 1.0
	v_rcp_f32_e32 v141, v140
	s_nop 0
	v_fma_f32 v142, -v140, v141, 1.0
	v_fmac_f32_e32 v141, v142, v141
	v_div_scale_f32 v142, vcc, 1.0, v129, 1.0
	v_mul_f32_e32 v143, v142, v141
	v_fma_f32 v165, -v140, v143, v142
	v_fmac_f32_e32 v143, v165, v141
	v_fma_f32 v140, -v140, v143, v142
	v_div_fmas_f32 v140, v140, v141, v143
	v_div_fixup_f32 v129, v140, v129, 1.0
	v_div_scale_f32 v140, s[26:27], v128, v128, 1.0
	v_rcp_f32_e32 v141, v140
	s_nop 0
	v_fma_f32 v142, -v140, v141, 1.0
	v_fmac_f32_e32 v141, v142, v141
	v_div_scale_f32 v142, vcc, 1.0, v128, 1.0
	v_mul_f32_e32 v143, v142, v141
	v_fma_f32 v165, -v140, v143, v142
	v_fmac_f32_e32 v143, v165, v141
	v_fma_f32 v140, -v140, v143, v142
	v_div_fmas_f32 v140, v140, v141, v143
	v_div_fixup_f32 v128, v140, v128, 1.0
	v_pk_mul_f32 v[138:139], v[138:139], v[128:129]
	v_mul_f32_e32 v128, 0xbfb8aa3b, v135
	v_exp_f32_e32 v135, v128
	v_pk_fma_f32 v[128:129], v[66:67], v[148:149], v[130:131] op_sel_hi:[1,0,1]
	v_pk_add_f32 v[130:131], v[134:135], 1.0 op_sel_hi:[1,0]
	s_nop 0
	v_div_scale_f32 v134, s[26:27], v131, v131, 1.0
	v_rcp_f32_e32 v135, v134
	s_nop 0
	v_fma_f32 v140, -v134, v135, 1.0
	v_fmac_f32_e32 v135, v140, v135
	v_div_scale_f32 v140, vcc, 1.0, v131, 1.0
	v_mul_f32_e32 v141, v140, v135
	v_fma_f32 v142, -v134, v141, v140
	v_fmac_f32_e32 v141, v142, v135
	v_fma_f32 v134, -v134, v141, v140
	v_div_fmas_f32 v134, v134, v135, v141
	v_div_fixup_f32 v131, v134, v131, 1.0
	v_div_scale_f32 v134, s[26:27], v130, v130, 1.0
	v_rcp_f32_e32 v135, v134
	s_nop 0
	v_fma_f32 v140, -v134, v135, 1.0
	v_fmac_f32_e32 v135, v140, v135
	v_div_scale_f32 v140, vcc, 1.0, v130, 1.0
	v_mul_f32_e32 v141, v140, v135
	v_fma_f32 v142, -v134, v141, v140
	v_fmac_f32_e32 v141, v142, v135
	v_fma_f32 v134, -v134, v141, v140
	v_div_fmas_f32 v134, v134, v135, v141
	v_div_fixup_f32 v130, v134, v130, 1.0
	v_pk_mul_f32 v[134:135], v[128:129], v[130:131]
	v_cvt_pk_bf16_f32 v130, v132, v133
	v_add_co_u32_e32 v132, vcc, 0x58000, v170
	v_cvt_pk_bf16_f32 v128, v136, v137
	v_cvt_pk_bf16_f32 v129, v138, v139
	v_cvt_pk_bf16_f32 v131, v134, v135
	v_addc_co_u32_e32 v133, vcc, 0, v171, vcc
	global_store_dwordx4 v[132:133], v[128:131], off

; DI unsigned pk(float lo, float hi) { f32x2 v = {lo, hi}; bf2_t b = __builtin_convertvector(v, bf2_t); return __builtin_bit_cast(unsigned, b); }
; DI void gemm_epilogue(const GemmDesc& g, f32x4 (&acc)[2][2][4][2], int brow, int bcol, int wr, int wc, int fr, int fq) {
;     ...
;       for (int bj = 0; bj < 2; ++bj) {
;         const int col = colb - 2048 + bj * HALF;
; #pragma unroll
;         for (int ai = 0; ai < 2; ++ai)
; #pragma unroll
;           for (int m = 0; m < 4; ++m) {
;             const int row = rowb + ai * HALF + m * 16;
;             const float ru = gld<float>(g.rowscale + row);
;             const f32x4 v0 = acc[ai][bj][m][0] * ru, v1 = acc[ai][bj][m][1] * ru;
;             u32x4 w; w.x = pk(v0[0], v0[1]); w.y = pk(v0[2], v0[3]); w.z = pk(v1[0], v1[1]); w.w = pk(v1[2], v1[3]);
;             gst<u32x4>(g.o1 + (size_t)row * 2048 + col, w);
;           }
.LBB0_418:
	s_cmp_lt_i32 s5, 8
	s_mov_b64 s[26:27], -1
	s_cbranch_scc1 .LBB0_420
	v_ashrrev_i32_e32 v167, 31, v166
	v_lshl_add_u64 v[128:129], v[166:167], 2, s[22:23]
	global_load_dword v236, v[128:129], off
	global_load_dword v237, v[128:129], off offset:64
	global_load_dword v238, v[128:129], off offset:128
	global_load_dword v239, v[128:129], off offset:192
	global_load_dword v240, v[128:129], off offset:512
	global_load_dword v241, v[128:129], off offset:576
	global_load_dword v242, v[128:129], off offset:640
	global_load_dword v243, v[128:129], off offset:704
	global_load_dword v132, v[128:129], off
	v_ashrrev_i32_e32 v165, 31, v164
	s_movk_i32 s26, 0xf000
	v_lshlrev_b64 v[130:131], 1, v[164:165]
	s_mov_b32 s27, -1
	v_lshl_add_u64 v[134:135], v[130:131], 0, s[26:27]
	s_mov_b64 s[26:27], 0x80000
	s_waitcnt vmcnt(0)
	v_pk_mul_f32 v[138:139], v[126:127], v[132:133] op_sel_hi:[1,0]
	v_pk_mul_f32 v[136:137], v[124:125], v[132:133] op_sel_hi:[1,0]
	v_pk_mul_f32 v[140:141], v[122:123], v[132:133] op_sel_hi:[1,0]
	v_pk_mul_f32 v[132:133], v[120:121], v[132:133] op_sel_hi:[1,0]
	v_cvt_pk_bf16_f32 v136, v136, v137
	v_cvt_pk_bf16_f32 v137, v138, v139
	v_cvt_pk_bf16_f32 v138, v132, v133
	v_lshlrev_b64 v[132:133], 12, v[166:167]
	v_lshl_add_u64 v[132:133], s[52:53], 0, v[132:133]
	v_cvt_pk_bf16_f32 v139, v140, v141
	v_lshl_add_u64 v[140:141], v[132:133], 0, v[134:135]
	global_store_dwordx4 v[140:141], v[136:139], off
	s_nop 1
	v_mov_b32_e32 v138, v237
	v_pk_mul_f32 v[140:141], v[118:119], v[138:139] op_sel_hi:[1,0]
	v_or_b32_e32 v136, 16, v166
	v_ashrrev_i32_e32 v137, 31, v136
	v_lshlrev_b64 v[136:137], 12, v[136:137]
	v_pk_mul_f32 v[142:143], v[116:117], v[138:139] op_sel_hi:[1,0]
	v_pk_mul_f32 v[168:169], v[114:115], v[138:139] op_sel_hi:[1,0]
	v_pk_mul_f32 v[170:171], v[112:113], v[138:139] op_sel_hi:[1,0]
	v_lshl_add_u64 v[136:137], s[52:53], 0, v[136:137]
	v_cvt_pk_bf16_f32 v138, v142, v143
	v_cvt_pk_bf16_f32 v139, v140, v141
	v_cvt_pk_bf16_f32 v140, v170, v171
	v_cvt_pk_bf16_f32 v141, v168, v169
	v_lshl_add_u64 v[142:143], v[136:137], 0, v[134:135]
	global_store_dwordx4 v[142:143], v[138:141], off
	s_nop 1
	v_mov_b32_e32 v140, v238
	v_pk_mul_f32 v[142:143], v[110:111], v[140:141] op_sel_hi:[1,0]
	v_or_b32_e32 v138, 32, v166
	v_ashrrev_i32_e32 v139, 31, v138
	v_lshlrev_b64 v[138:139], 12, v[138:139]
	v_pk_mul_f32 v[168:169], v[108:109], v[140:141] op_sel_hi:[1,0]
	v_pk_mul_f32 v[170:171], v[106:107], v[140:141] op_sel_hi:[1,0]
	v_pk_mul_f32 v[172:173], v[104:105], v[140:141] op_sel_hi:[1,0]
	v_lshl_add_u64 v[138:139], s[52:53], 0, v[138:139]
	v_cvt_pk_bf16_f32 v140, v168, v169
	v_cvt_pk_bf16_f32 v141, v142, v143
	v_cvt_pk_bf16_f32 v142, v172, v173
	v_cvt_pk_bf16_f32 v143, v170, v171
	v_lshl_add_u64 v[168:169], v[138:139], 0, v[134:135]
	global_store_dwordx4 v[168:169], v[140:143], off
	s_nop 1
	v_mov_b32_e32 v142, v239
	v_pk_mul_f32 v[170:171], v[102:103], v[142:143] op_sel_hi:[1,0]
	v_or_b32_e32 v140, 48, v166
	v_ashrrev_i32_e32 v141, 31, v140
	v_lshlrev_b64 v[140:141], 12, v[140:141]
	v_pk_mul_f32 v[168:169], v[100:101], v[142:143] op_sel_hi:[1,0]
	v_pk_mul_f32 v[172:173], v[98:99], v[142:143] op_sel_hi:[1,0]
	v_pk_mul_f32 v[142:143], v[96:97], v[142:143] op_sel_hi:[1,0]
	v_lshl_add_u64 v[140:141], s[52:53], 0, v[140:141]
	v_cvt_pk_bf16_f32 v168, v168, v169
	v_cvt_pk_bf16_f32 v169, v170, v171
	v_cvt_pk_bf16_f32 v170, v142, v143
	v_cvt_pk_bf16_f32 v171, v172, v173
	v_lshl_add_u64 v[142:143], v[140:141], 0, v[134:135]
	global_store_dwordx4 v[142:143], v[168:171], off
	s_nop 1
	v_mov_b32_e32 v142, v240
	v_pk_mul_f32 v[172:173], v[90:91], v[142:143] op_sel_hi:[1,0]
	v_pk_mul_f32 v[170:171], v[94:95], v[142:143] op_sel_hi:[1,0]
	v_pk_mul_f32 v[168:169], v[92:93], v[142:143] op_sel_hi:[1,0]
	v_pk_mul_f32 v[142:143], v[88:89], v[142:143] op_sel_hi:[1,0]
	v_cvt_pk_bf16_f32 v168, v168, v169
	v_cvt_pk_bf16_f32 v169, v170, v171
	v_cvt_pk_bf16_f32 v170, v142, v143
	v_lshl_add_u64 v[142:143], v[132:133], 0, s[26:27]
	v_cvt_pk_bf16_f32 v171, v172, v173
	v_lshl_add_u64 v[172:173], v[142:143], 0, v[134:135]
	global_store_dwordx4 v[172:173], v[168:171], off
	s_nop 1
	v_mov_b32_e32 v148, v241
	s_mov_b64 s[26:27], 0x90000
	v_pk_mul_f32 v[168:169], v[86:87], v[148:149] op_sel_hi:[1,0]
	v_pk_mul_f32 v[170:171], v[84:85], v[148:149] op_sel_hi:[1,0]
	v_pk_mul_f32 v[174:175], v[82:83], v[148:149] op_sel_hi:[1,0]
	v_pk_mul_f32 v[172:173], v[80:81], v[148:149] op_sel_hi:[1,0]
	v_cvt_pk_bf16_f32 v170, v170, v171
	v_cvt_pk_bf16_f32 v171, v168, v169
	v_lshl_add_u64 v[168:169], v[132:133], 0, s[26:27]
	v_cvt_pk_bf16_f32 v172, v172, v173
	v_cvt_pk_bf16_f32 v173, v174, v175
	v_lshl_add_u64 v[174:175], v[168:169], 0, v[134:135]
	global_store_dwordx4 v[174:175], v[170:173], off
	s_nop 1
	v_mov_b32_e32 v148, v242
	s_mov_b64 s[26:27], 0xa0000
	v_pk_mul_f32 v[170:171], v[78:79], v[148:149] op_sel_hi:[1,0]
	v_pk_mul_f32 v[172:173], v[76:77], v[148:149] op_sel_hi:[1,0]
	v_pk_mul_f32 v[176:177], v[74:75], v[148:149] op_sel_hi:[1,0]
	v_pk_mul_f32 v[174:175], v[72:73], v[148:149] op_sel_hi:[1,0]
	v_cvt_pk_bf16_f32 v172, v172, v173
	v_cvt_pk_bf16_f32 v173, v170, v171
	v_lshl_add_u64 v[170:171], v[132:133], 0, s[26:27]
	v_cvt_pk_bf16_f32 v174, v174, v175
	v_cvt_pk_bf16_f32 v175, v176, v177
	v_lshl_add_u64 v[176:177], v[170:171], 0, v[134:135]
	global_store_dwordx4 v[176:177], v[172:175], off
	s_nop 1
	v_mov_b32_e32 v148, v243
	s_mov_b64 s[26:27], 0xb0000
	v_pk_mul_f32 v[172:173], v[70:71], v[148:149] op_sel_hi:[1,0]
	v_pk_mul_f32 v[174:175], v[68:69], v[148:149] op_sel_hi:[1,0]
	v_pk_mul_f32 v[178:179], v[66:67], v[148:149] op_sel_hi:[1,0]
	v_pk_mul_f32 v[176:177], v[64:65], v[148:149] op_sel_hi:[1,0]
; DI unsigned pk(float lo, float hi) { f32x2 v = {lo, hi}; bf2_t b = __builtin_convertvector(v, bf2_t); return __builtin_bit_cast(unsigned, b); }
; DI void gemm_epilogue(const GemmDesc& g, f32x4 (&acc)[2][2][4][2], int brow, int bcol, int wr, int wc, int fr, int fq) {
;     ...
;       for (int bj = 0; bj < 2; ++bj) {
;         const int col = colb - 2048 + bj * HALF;
; #pragma unroll
;         for (int ai = 0; ai < 2; ++ai)
; #pragma unroll
;           for (int m = 0; m < 4; ++m) {
;             const int row = rowb + ai * HALF + m * 16;
;             const float ru = gld<float>(g.rowscale + row);
;             const f32x4 v0 = acc[ai][bj][m][0] * ru, v1 = acc[ai][bj][m][1] * ru;
;             u32x4 w; w.x = pk(v0[0], v0[1]); w.y = pk(v0[2], v0[3]); w.z = pk(v1[0], v1[1]); w.w = pk(v1[2], v1[3]);
;             gst<u32x4>(g.o1 + (size_t)row * 2048 + col, w);
;           }
	v_cvt_pk_bf16_f32 v174, v174, v175
	v_cvt_pk_bf16_f32 v175, v172, v173
	v_lshl_add_u64 v[172:173], v[132:133], 0, s[26:27]
	v_cvt_pk_bf16_f32 v176, v176, v177
	v_cvt_pk_bf16_f32 v177, v178, v179
	v_lshl_add_u64 v[134:135], v[172:173], 0, v[134:135]
	global_store_dwordx4 v[134:135], v[174:177], off
	s_nop 1
	v_mov_b32_e32 v134, v236
	s_movk_i32 s26, 0xf100
	s_mov_b32 s27, -1
	v_lshl_add_u64 v[130:131], v[130:131], 0, s[26:27]
	v_lshl_add_u64 v[132:133], v[132:133], 0, v[130:131]
	v_lshl_add_u64 v[136:137], v[136:137], 0, v[130:131]
	s_mov_b64 s[26:27], 0
	v_pk_mul_f32 v[176:177], v[62:63], v[134:135] op_sel_hi:[1,0]
	v_pk_mul_f32 v[174:175], v[60:61], v[134:135] op_sel_hi:[1,0]
	v_pk_mul_f32 v[178:179], v[58:59], v[134:135] op_sel_hi:[1,0]
	v_pk_mul_f32 v[134:135], v[56:57], v[134:135] op_sel_hi:[1,0]
	v_cvt_pk_bf16_f32 v174, v174, v175
	v_cvt_pk_bf16_f32 v175, v176, v177
	v_cvt_pk_bf16_f32 v176, v134, v135
	v_cvt_pk_bf16_f32 v177, v178, v179
	global_store_dwordx4 v[132:133], v[174:177], off
	s_nop 1
	v_mov_b32_e32 v132, v237
	v_pk_mul_f32 v[134:135], v[54:55], v[132:133] op_sel_hi:[1,0]
	v_pk_mul_f32 v[174:175], v[52:53], v[132:133] op_sel_hi:[1,0]
	v_pk_mul_f32 v[176:177], v[50:51], v[132:133] op_sel_hi:[1,0]
	v_pk_mul_f32 v[178:179], v[48:49], v[132:133] op_sel_hi:[1,0]
	v_cvt_pk_bf16_f32 v132, v174, v175
	v_cvt_pk_bf16_f32 v133, v134, v135
	v_cvt_pk_bf16_f32 v134, v178, v179
	v_cvt_pk_bf16_f32 v135, v176, v177
	global_store_dwordx4 v[136:137], v[132:135], off
	s_nop 1
	v_mov_b32_e32 v132, v238
	v_pk_mul_f32 v[136:137], v[44:45], v[132:133] op_sel_hi:[1,0]
	v_pk_mul_f32 v[134:135], v[46:47], v[132:133] op_sel_hi:[1,0]
	v_pk_mul_f32 v[174:175], v[42:43], v[132:133] op_sel_hi:[1,0]
	v_pk_mul_f32 v[176:177], v[40:41], v[132:133] op_sel_hi:[1,0]
	v_cvt_pk_bf16_f32 v132, v136, v137
	v_cvt_pk_bf16_f32 v133, v134, v135
	v_cvt_pk_bf16_f32 v134, v176, v177
	v_cvt_pk_bf16_f32 v135, v174, v175
	v_lshl_add_u64 v[136:137], v[138:139], 0, v[130:131]
	global_store_dwordx4 v[136:137], v[132:135], off
	s_nop 1
	v_mov_b32_e32 v132, v239
	v_pk_mul_f32 v[136:137], v[36:37], v[132:133] op_sel_hi:[1,0]
	v_pk_mul_f32 v[134:135], v[38:39], v[132:133] op_sel_hi:[1,0]
	v_pk_mul_f32 v[138:139], v[34:35], v[132:133] op_sel_hi:[1,0]
	v_pk_mul_f32 v[174:175], v[32:33], v[132:133] op_sel_hi:[1,0]
	v_cvt_pk_bf16_f32 v132, v136, v137
	v_cvt_pk_bf16_f32 v133, v134, v135
	v_cvt_pk_bf16_f32 v134, v174, v175
	v_cvt_pk_bf16_f32 v135, v138, v139
	v_lshl_add_u64 v[136:137], v[140:141], 0, v[130:131]
	global_store_dwordx4 v[136:137], v[132:135], off
	s_nop 1
	v_mov_b32_e32 v132, v240
	v_pk_mul_f32 v[136:137], v[28:29], v[132:133] op_sel_hi:[1,0]
	v_pk_mul_f32 v[134:135], v[30:31], v[132:133] op_sel_hi:[1,0]
	v_pk_mul_f32 v[138:139], v[26:27], v[132:133] op_sel_hi:[1,0]
	v_pk_mul_f32 v[140:141], v[24:25], v[132:133] op_sel_hi:[1,0]
	v_cvt_pk_bf16_f32 v132, v136, v137
	v_cvt_pk_bf16_f32 v133, v134, v135
	v_cvt_pk_bf16_f32 v134, v140, v141
	v_cvt_pk_bf16_f32 v135, v138, v139
	v_lshl_add_u64 v[136:137], v[142:143], 0, v[130:131]
	global_store_dwordx4 v[136:137], v[132:135], off
	s_nop 1
	v_mov_b32_e32 v132, v241
	v_pk_mul_f32 v[136:137], v[20:21], v[132:133] op_sel_hi:[1,0]
	v_pk_mul_f32 v[134:135], v[22:23], v[132:133] op_sel_hi:[1,0]
	v_pk_mul_f32 v[138:139], v[18:19], v[132:133] op_sel_hi:[1,0]
	v_pk_mul_f32 v[140:141], v[16:17], v[132:133] op_sel_hi:[1,0]
	v_cvt_pk_bf16_f32 v132, v136, v137
	v_cvt_pk_bf16_f32 v133, v134, v135
	v_cvt_pk_bf16_f32 v134, v140, v141
	v_cvt_pk_bf16_f32 v135, v138, v139
	v_lshl_add_u64 v[136:137], v[168:169], 0, v[130:131]
	global_store_dwordx4 v[136:137], v[132:135], off
	s_nop 1
	v_mov_b32_e32 v132, v242
	v_pk_mul_f32 v[136:137], v[12:13], v[132:133] op_sel_hi:[1,0]
	v_pk_mul_f32 v[134:135], v[14:15], v[132:133] op_sel_hi:[1,0]
	v_pk_mul_f32 v[138:139], v[10:11], v[132:133] op_sel_hi:[1,0]
	v_pk_mul_f32 v[140:141], v[8:9], v[132:133] op_sel_hi:[1,0]
	v_cvt_pk_bf16_f32 v132, v136, v137
	v_cvt_pk_bf16_f32 v133, v134, v135
	v_cvt_pk_bf16_f32 v134, v140, v141
	v_cvt_pk_bf16_f32 v135, v138, v139
	v_lshl_add_u64 v[136:137], v[170:171], 0, v[130:131]
	global_store_dwordx4 v[136:137], v[132:135], off
	s_nop 1
	v_mov_b32_e32 v128, v243
	v_pk_mul_f32 v[136:137], v[2:3], v[128:129] op_sel_hi:[1,0]
	v_pk_mul_f32 v[134:135], v[6:7], v[128:129] op_sel_hi:[1,0]
	v_pk_mul_f32 v[132:133], v[4:5], v[128:129] op_sel_hi:[1,0]
	v_pk_mul_f32 v[128:129], v[0:1], v[128:129] op_sel_hi:[1,0]
	v_cvt_pk_bf16_f32 v132, v132, v133
	v_cvt_pk_bf16_f32 v133, v134, v135
	v_cvt_pk_bf16_f32 v134, v128, v129
	v_cvt_pk_bf16_f32 v135, v136, v137
	v_lshl_add_u64 v[128:129], v[172:173], 0, v[130:131]
	global_store_dwordx4 v[128:129], v[132:135], off
; DI unsigned pk(float lo, float hi) { f32x2 v = {lo, hi}; bf2_t b = __builtin_convertvector(v, bf2_t); return __builtin_bit_cast(unsigned, b); }
; DI void gemm_epilogue(const GemmDesc& g, f32x4 (&acc)[2][2][4][2], int brow, int bcol, int wr, int wc, int fr, int fq) {
;     ...
;     if (bcol < 2048) {
;       const float sc = (bcol < 1024) ? 0.0625f : 1.0f;
;       const int d0 = wc * 32 + 8 * fq;
;       float fr_[8];
; #pragma unroll
;       for (int j = 0; j < 8; ++j) fr_[j] = exp2f(-(float)(d0 + j) * (13.287712379549449f / 128.0f)) * 0.15915494309189535f;
; #pragma unroll
;       for (int ai = 0; ai < 2; ++ai)
; #pragma unroll
;         for (int m = 0; m < 4; ++m) {
;           const int row = rowb + ai * HALF + m * 16;
;           const float pf = (float)gld<int>(g.pos + row);
;           const float scr = sc * gld<float>(g.rowscale + row);
;           float y1[8], y2[8];
; #pragma unroll
;           for (int n = 0; n < 2; ++n) {
;             const f32x4 x1 = acc[ai][0][m][n], x2 = acc[ai][1][m][n];
; #pragma unroll
;             for (int j = 0; j < 4; ++j) {
;               float rev = pf * fr_[4 * n + j]; rev = rev - rintf(rev);
;               const float sn = __builtin_amdgcn_sinf(rev), cs = __builtin_amdgcn_cosf(rev);
;               y1[4 * n + j] = (x1[j] * cs - x2[j] * sn) * scr; y2[4 * n + j] = (x2[j] * cs + x1[j] * sn) * scr;
;             }
;           }
;           u32x4 w1, w2;
;           w1.x = pk(y1[0], y1[1]); w1.y = pk(y1[2], y1[3]); w1.z = pk(y1[4], y1[5]); w1.w = pk(y1[6], y1[7]);
;           w2.x = pk(y2[0], y2[1]); w2.y = pk(y2[2], y2[3]); w2.z = pk(y2[4], y2[5]); w2.w = pk(y2[6], y2[7]);
;           bf16_t* op = g.o0 + (size_t)row * 2048 + bcol + d0;
;           gst<u32x4>(op, w1); gst<u32x4>(op + 128, w2);
.LBB0_420:
	s_andn2_b64 vcc, exec, s[26:27]
	s_cbranch_vccnz .LBB0_422
	s_cmp_lt_i32 s5, 4
	s_cselect_b64 vcc, -1, 0
	v_mov_b32_e32 v128, 0x3d800000
	v_ashrrev_i32_e32 v167, 31, v166
	v_readlane_b32 s26, v255, 31
	v_cndmask_b32_e32 v165, 1.0, v128, vcc
	v_lshlrev_b64 v[128:129], 2, v[166:167]
	v_readlane_b32 s27, v255, 32
	v_lshl_add_u64 v[138:139], s[22:23], 0, v[128:129]
	s_ashr_i32 s87, s86, 31
	v_lshl_add_u64 v[136:137], s[26:27], 0, v[128:129]
	global_load_dword v236, v[136:137], off
	global_load_dword v237, v[136:137], off offset:64
	global_load_dword v238, v[136:137], off offset:128
	global_load_dword v239, v[136:137], off offset:192
	global_load_dword v240, v[136:137], off offset:512
	global_load_dword v241, v[136:137], off offset:576
	global_load_dword v242, v[136:137], off offset:640
	global_load_dword v243, v[136:137], off offset:704
	global_load_dword v130, v[136:137], off
	global_load_dword v244, v[138:139], off
	global_load_dword v245, v[138:139], off offset:64
	global_load_dword v246, v[138:139], off offset:128
	global_load_dword v247, v[138:139], off offset:192
	global_load_dword v248, v[138:139], off offset:512
	global_load_dword v249, v[138:139], off offset:576
	global_load_dword v251, v[138:139], off offset:640
	global_load_dword v252, v[138:139], off offset:704
	global_load_dword v128, v[138:139], off
	s_lshl_b64 s[26:27], s[86:87], 1
	s_mov_b32 s5, 0x80000
	s_waitcnt vmcnt(0)
	v_cvt_f32_i32_e32 v148, v130
	v_mul_f32_e32 v128, v165, v128
	v_mul_f32_e32 v129, v220, v148
	v_rndne_f32_e32 v129, v129
	v_fma_f32 v129, v220, v148, -v129
	v_sin_f32_e32 v130, v129
	v_cos_f32_e32 v132, v129
	v_mul_f32_e32 v129, v221, v148
	v_rndne_f32_e32 v129, v129
	v_fma_f32 v129, v221, v148, -v129
	v_sin_f32_e32 v131, v129
	v_cos_f32_e32 v133, v129
	v_pk_mul_f32 v[134:135], v[60:61], v[130:131]
	v_pk_mul_f32 v[130:131], v[124:125], v[130:131]
	v_pk_fma_f32 v[134:135], v[124:125], v[132:133], v[134:135] neg_lo:[0,0,1] neg_hi:[0,0,1]
	v_pk_fma_f32 v[130:131], v[60:61], v[132:133], v[130:131]
	v_pk_mul_f32 v[134:135], v[128:129], v[134:135] op_sel_hi:[0,1]
	v_pk_mul_f32 v[132:133], v[128:129], v[130:131] op_sel_hi:[0,1]
	v_mul_f32_e32 v129, v222, v148
	v_rndne_f32_e32 v129, v129
	v_fma_f32 v129, v222, v148, -v129
	v_sin_f32_e32 v130, v129
	v_cos_f32_e32 v140, v129
	v_mul_f32_e32 v129, v223, v148
	v_rndne_f32_e32 v129, v129
	v_fma_f32 v129, v223, v148, -v129
	v_sin_f32_e32 v131, v129
	v_cos_f32_e32 v141, v129
	v_cvt_pk_bf16_f32 v132, v132, v133
	v_pk_mul_f32 v[142:143], v[62:63], v[130:131]
	v_pk_mul_f32 v[130:131], v[126:127], v[130:131]
	v_pk_fma_f32 v[142:143], v[126:127], v[140:141], v[142:143] neg_lo:[0,0,1] neg_hi:[0,0,1]
	v_pk_fma_f32 v[130:131], v[62:63], v[140:141], v[130:131]
	v_pk_mul_f32 v[142:143], v[128:129], v[142:143] op_sel_hi:[0,1]
	v_pk_mul_f32 v[140:141], v[128:129], v[130:131] op_sel_hi:[0,1]
	v_mul_f32_e32 v129, v224, v148
	v_rndne_f32_e32 v129, v129
	v_fma_f32 v129, v224, v148, -v129
	v_sin_f32_e32 v130, v129
	v_cos_f32_e32 v168, v129
	v_mul_f32_e32 v129, v225, v148
	v_rndne_f32_e32 v129, v129
	v_fma_f32 v129, v225, v148, -v129
	v_sin_f32_e32 v131, v129
	v_cos_f32_e32 v169, v129
	v_cvt_pk_bf16_f32 v133, v140, v141
	v_lshlrev_b64 v[140:141], 12, v[166:167]
	v_pk_mul_f32 v[170:171], v[56:57], v[130:131]
	v_lshl_add_u64 v[140:141], s[64:65], 0, v[140:141]
	v_pk_fma_f32 v[170:171], v[120:121], v[168:169], v[170:171] neg_lo:[0,0,1] neg_hi:[0,0,1]
	v_pk_mul_f32 v[168:169], v[56:57], v[168:169]
	v_pk_mul_f32 v[170:171], v[128:129], v[170:171] op_sel_hi:[0,1]
	v_pk_fma_f32 v[130:131], v[120:121], v[130:131], v[168:169]
	v_lshl_add_u64 v[140:141], v[140:141], 0, s[26:27]
	v_pk_mul_f32 v[168:169], v[128:129], v[130:131] op_sel_hi:[0,1]
	v_mul_f32_e32 v129, v226, v148
	v_rndne_f32_e32 v129, v129
	v_fma_f32 v129, v226, v148, -v129
	v_sin_f32_e32 v130, v129
	v_cos_f32_e32 v172, v129
	v_mul_f32_e32 v129, v227, v148
	v_rndne_f32_e32 v129, v129
	v_fma_f32 v129, v227, v148, -v129
	v_sin_f32_e32 v131, v129
	v_cos_f32_e32 v173, v129
	v_lshlrev_b32_e32 v148, 1, v158
	v_lshl_add_u64 v[140:141], v[140:141], 0, v[148:149]
	v_pk_mul_f32 v[174:175], v[58:59], v[130:131]
	s_nop 0
	v_pk_fma_f32 v[174:175], v[122:123], v[172:173], v[174:175] neg_lo:[0,0,1] neg_hi:[0,0,1]
	v_pk_mul_f32 v[172:173], v[58:59], v[172:173]
	v_pk_mul_f32 v[174:175], v[128:129], v[174:175] op_sel_hi:[0,1]
	v_pk_fma_f32 v[130:131], v[122:123], v[130:131], v[172:173]
	s_nop 0
	v_pk_mul_f32 v[172:173], v[128:129], v[130:131] op_sel_hi:[0,1]
	v_cvt_pk_bf16_f32 v128, v134, v135
	v_cvt_pk_bf16_f32 v129, v142, v143
	v_cvt_pk_bf16_f32 v130, v170, v171
	v_cvt_pk_bf16_f32 v131, v174, v175
	v_cvt_pk_bf16_f32 v134, v168, v169
	v_cvt_pk_bf16_f32 v135, v172, v173
	global_store_dwordx4 v[140:141], v[128:131], off
	global_store_dwordx4 v[140:141], v[132:135], off offset:256
	s_nop 1
	v_mov_b32_e32 v128, v237
	v_or_b32_e32 v142, 16, v166
	v_ashrrev_i32_e32 v143, 31, v142
	v_lshlrev_b64 v[142:143], 12, v[142:143]
	v_lshl_add_u64 v[142:143], s[64:65], 0, v[142:143]
	v_lshl_add_u64 v[142:143], v[142:143], 0, s[26:27]
	v_lshl_add_u64 v[142:143], v[142:143], 0, v[148:149]
	v_cvt_f32_i32_e32 v129, v128
	s_nop 1
	v_mov_b32_e32 v128, v245
	v_mul_f32_e32 v130, v220, v129
	v_rndne_f32_e32 v130, v130
	v_fma_f32 v131, v220, v129, -v130
	v_sin_f32_e32 v130, v131
	v_cos_f32_e32 v132, v131
	v_mul_f32_e32 v131, v221, v129
	v_rndne_f32_e32 v131, v131
	v_fma_f32 v133, v221, v129, -v131
	v_sin_f32_e32 v131, v133
	v_cos_f32_e32 v133, v133
	v_pk_mul_f32 v[134:135], v[52:53], v[130:131]
	v_pk_mul_f32 v[130:131], v[116:117], v[130:131]
	v_pk_fma_f32 v[134:135], v[116:117], v[132:133], v[134:135] neg_lo:[0,0,1] neg_hi:[0,0,1]
; DI unsigned pk(float lo, float hi) { f32x2 v = {lo, hi}; bf2_t b = __builtin_convertvector(v, bf2_t); return __builtin_bit_cast(unsigned, b); }
; DI void gemm_epilogue(const GemmDesc& g, f32x4 (&acc)[2][2][4][2], int brow, int bcol, int wr, int wc, int fr, int fq) {
;     ...
;           const int row = rowb + ai * HALF + m * 16;
;           const float pf = (float)gld<int>(g.pos + row);
;           const float scr = sc * gld<float>(g.rowscale + row);
;           float y1[8], y2[8];
; #pragma unroll
;           for (int n = 0; n < 2; ++n) {
;             const f32x4 x1 = acc[ai][0][m][n], x2 = acc[ai][1][m][n];
; #pragma unroll
;             for (int j = 0; j < 4; ++j) {
;               float rev = pf * fr_[4 * n + j]; rev = rev - rintf(rev);
;               const float sn = __builtin_amdgcn_sinf(rev), cs = __builtin_amdgcn_cosf(rev);
;               y1[4 * n + j] = (x1[j] * cs - x2[j] * sn) * scr; y2[4 * n + j] = (x2[j] * cs + x1[j] * sn) * scr;
;             }
;           }
;           u32x4 w1, w2;
;           w1.x = pk(y1[0], y1[1]); w1.y = pk(y1[2], y1[3]); w1.z = pk(y1[4], y1[5]); w1.w = pk(y1[6], y1[7]);
;           w2.x = pk(y2[0], y2[1]); w2.y = pk(y2[2], y2[3]); w2.z = pk(y2[4], y2[5]); w2.w = pk(y2[6], y2[7]);
;           bf16_t* op = g.o0 + (size_t)row * 2048 + bcol + d0;
;           gst<u32x4>(op, w1); gst<u32x4>(op + 128, w2);
	v_pk_fma_f32 v[130:131], v[52:53], v[132:133], v[130:131]
	v_mul_f32_e32 v128, v165, v128
	v_pk_mul_f32 v[132:133], v[128:129], v[130:131] op_sel_hi:[0,1]
	v_mul_f32_e32 v130, v222, v129
	v_rndne_f32_e32 v130, v130
	v_fma_f32 v131, v222, v129, -v130
	v_sin_f32_e32 v130, v131
	v_cos_f32_e32 v168, v131
	v_mul_f32_e32 v131, v223, v129
	v_rndne_f32_e32 v131, v131
	v_fma_f32 v167, v223, v129, -v131
	v_sin_f32_e32 v131, v167
	v_cos_f32_e32 v169, v167
	v_pk_mul_f32 v[134:135], v[128:129], v[134:135] op_sel_hi:[0,1]
	v_cvt_pk_bf16_f32 v132, v132, v133
	v_pk_mul_f32 v[170:171], v[54:55], v[130:131]
	v_pk_mul_f32 v[130:131], v[118:119], v[130:131]
	v_pk_fma_f32 v[170:171], v[118:119], v[168:169], v[170:171] neg_lo:[0,0,1] neg_hi:[0,0,1]
	v_pk_fma_f32 v[130:131], v[54:55], v[168:169], v[130:131]
	v_pk_mul_f32 v[170:171], v[128:129], v[170:171] op_sel_hi:[0,1]
	v_pk_mul_f32 v[168:169], v[128:129], v[130:131] op_sel_hi:[0,1]
	v_mul_f32_e32 v130, v224, v129
	v_rndne_f32_e32 v130, v130
	v_fma_f32 v131, v224, v129, -v130
	v_sin_f32_e32 v130, v131
	v_cos_f32_e32 v172, v131
	v_mul_f32_e32 v131, v225, v129
	v_rndne_f32_e32 v131, v131
	v_fma_f32 v167, v225, v129, -v131
	v_sin_f32_e32 v131, v167
	v_cos_f32_e32 v173, v167
	v_cvt_pk_bf16_f32 v133, v168, v169
	v_pk_mul_f32 v[174:175], v[48:49], v[130:131]
	s_nop 0
	v_pk_fma_f32 v[174:175], v[112:113], v[172:173], v[174:175] neg_lo:[0,0,1] neg_hi:[0,0,1]
	v_pk_mul_f32 v[172:173], v[48:49], v[172:173]
	v_pk_mul_f32 v[174:175], v[128:129], v[174:175] op_sel_hi:[0,1]
	v_pk_fma_f32 v[130:131], v[112:113], v[130:131], v[172:173]
	s_nop 0
	v_pk_mul_f32 v[172:173], v[128:129], v[130:131] op_sel_hi:[0,1]
	v_mul_f32_e32 v130, v226, v129
	v_rndne_f32_e32 v130, v130
	v_fma_f32 v131, v226, v129, -v130
	v_sin_f32_e32 v130, v131
	v_cos_f32_e32 v176, v131
	v_mul_f32_e32 v131, v227, v129
	v_rndne_f32_e32 v131, v131
	v_fma_f32 v129, v227, v129, -v131
	v_sin_f32_e32 v131, v129
	v_cos_f32_e32 v177, v129
	v_pk_mul_f32 v[178:179], v[50:51], v[130:131]
	s_nop 0
	v_pk_fma_f32 v[178:179], v[114:115], v[176:177], v[178:179] neg_lo:[0,0,1] neg_hi:[0,0,1]
	v_pk_mul_f32 v[176:177], v[50:51], v[176:177]
	v_pk_mul_f32 v[178:179], v[128:129], v[178:179] op_sel_hi:[0,1]
	v_pk_fma_f32 v[130:131], v[114:115], v[130:131], v[176:177]
	s_nop 0
	v_pk_mul_f32 v[176:177], v[128:129], v[130:131] op_sel_hi:[0,1]
	v_cvt_pk_bf16_f32 v128, v134, v135
	v_cvt_pk_bf16_f32 v129, v170, v171
	v_cvt_pk_bf16_f32 v130, v174, v175
	v_cvt_pk_bf16_f32 v131, v178, v179
	v_cvt_pk_bf16_f32 v134, v172, v173
	v_cvt_pk_bf16_f32 v135, v176, v177
	global_store_dwordx4 v[142:143], v[128:131], off
	global_store_dwordx4 v[142:143], v[132:135], off offset:256
	s_nop 1
	v_mov_b32_e32 v128, v238
	v_or_b32_e32 v142, 32, v166
	v_ashrrev_i32_e32 v143, 31, v142
	v_lshlrev_b64 v[142:143], 12, v[142:143]
	v_lshl_add_u64 v[142:143], s[64:65], 0, v[142:143]
	v_lshl_add_u64 v[142:143], v[142:143], 0, s[26:27]
	v_lshl_add_u64 v[142:143], v[142:143], 0, v[148:149]
	v_cvt_f32_i32_e32 v129, v128
	s_nop 1
	v_mov_b32_e32 v128, v246
	v_mul_f32_e32 v130, v220, v129
	v_rndne_f32_e32 v130, v130
	v_fma_f32 v131, v220, v129, -v130
	v_sin_f32_e32 v130, v131
	v_cos_f32_e32 v132, v131
	v_mul_f32_e32 v131, v221, v129
	v_rndne_f32_e32 v131, v131
	v_fma_f32 v133, v221, v129, -v131
	v_sin_f32_e32 v131, v133
	v_cos_f32_e32 v133, v133
	v_pk_mul_f32 v[134:135], v[44:45], v[130:131]
	v_pk_mul_f32 v[130:131], v[108:109], v[130:131]
	v_pk_fma_f32 v[134:135], v[108:109], v[132:133], v[134:135] neg_lo:[0,0,1] neg_hi:[0,0,1]
	v_pk_fma_f32 v[130:131], v[44:45], v[132:133], v[130:131]
	v_mul_f32_e32 v128, v165, v128
	v_pk_mul_f32 v[132:133], v[128:129], v[130:131] op_sel_hi:[0,1]
	v_mul_f32_e32 v130, v222, v129
	v_rndne_f32_e32 v130, v130
	v_fma_f32 v131, v222, v129, -v130
	v_sin_f32_e32 v130, v131
	v_cos_f32_e32 v168, v131
	v_mul_f32_e32 v131, v223, v129
	v_rndne_f32_e32 v131, v131
	v_fma_f32 v167, v223, v129, -v131
	v_sin_f32_e32 v131, v167
	v_cos_f32_e32 v169, v167
	v_pk_mul_f32 v[134:135], v[128:129], v[134:135] op_sel_hi:[0,1]
	v_cvt_pk_bf16_f32 v132, v132, v133
	v_pk_mul_f32 v[170:171], v[46:47], v[130:131]
	v_pk_mul_f32 v[130:131], v[110:111], v[130:131]
	v_pk_fma_f32 v[170:171], v[110:111], v[168:169], v[170:171] neg_lo:[0,0,1] neg_hi:[0,0,1]
	v_pk_fma_f32 v[130:131], v[46:47], v[168:169], v[130:131]
	v_pk_mul_f32 v[170:171], v[128:129], v[170:171] op_sel_hi:[0,1]
	v_pk_mul_f32 v[168:169], v[128:129], v[130:131] op_sel_hi:[0,1]
	v_mul_f32_e32 v130, v224, v129
	v_rndne_f32_e32 v130, v130
	v_fma_f32 v131, v224, v129, -v130
	v_sin_f32_e32 v130, v131
	v_cos_f32_e32 v172, v131
	v_mul_f32_e32 v131, v225, v129
	v_rndne_f32_e32 v131, v131
	v_fma_f32 v167, v225, v129, -v131
	v_sin_f32_e32 v131, v167
	v_cos_f32_e32 v173, v167
	v_cvt_pk_bf16_f32 v133, v168, v169
	v_pk_mul_f32 v[174:175], v[40:41], v[130:131]
	s_nop 0
	v_pk_fma_f32 v[174:175], v[104:105], v[172:173], v[174:175] neg_lo:[0,0,1] neg_hi:[0,0,1]
	v_pk_mul_f32 v[172:173], v[40:41], v[172:173]
	v_pk_mul_f32 v[174:175], v[128:129], v[174:175] op_sel_hi:[0,1]
	v_pk_fma_f32 v[130:131], v[104:105], v[130:131], v[172:173]
	s_nop 0
	v_pk_mul_f32 v[172:173], v[128:129], v[130:131] op_sel_hi:[0,1]
	v_mul_f32_e32 v130, v226, v129
	v_rndne_f32_e32 v130, v130
	v_fma_f32 v131, v226, v129, -v130
	v_sin_f32_e32 v130, v131
	v_cos_f32_e32 v176, v131
	v_mul_f32_e32 v131, v227, v129
	v_rndne_f32_e32 v131, v131
	v_fma_f32 v129, v227, v129, -v131
	v_sin_f32_e32 v131, v129
	v_cos_f32_e32 v177, v129
	v_pk_mul_f32 v[178:179], v[42:43], v[130:131]
	s_nop 0
	v_pk_fma_f32 v[178:179], v[106:107], v[176:177], v[178:179] neg_lo:[0,0,1] neg_hi:[0,0,1]
	v_pk_mul_f32 v[176:177], v[42:43], v[176:177]
; DI unsigned pk(float lo, float hi) { f32x2 v = {lo, hi}; bf2_t b = __builtin_convertvector(v, bf2_t); return __builtin_bit_cast(unsigned, b); }
; DI void gemm_epilogue(const GemmDesc& g, f32x4 (&acc)[2][2][4][2], int brow, int bcol, int wr, int wc, int fr, int fq) {
;     ...
;           const int row = rowb + ai * HALF + m * 16;
;           const float pf = (float)gld<int>(g.pos + row);
;           const float scr = sc * gld<float>(g.rowscale + row);
;           float y1[8], y2[8];
; #pragma unroll
;           for (int n = 0; n < 2; ++n) {
;             const f32x4 x1 = acc[ai][0][m][n], x2 = acc[ai][1][m][n];
; #pragma unroll
;             for (int j = 0; j < 4; ++j) {
;               float rev = pf * fr_[4 * n + j]; rev = rev - rintf(rev);
;               const float sn = __builtin_amdgcn_sinf(rev), cs = __builtin_amdgcn_cosf(rev);
;               y1[4 * n + j] = (x1[j] * cs - x2[j] * sn) * scr; y2[4 * n + j] = (x2[j] * cs + x1[j] * sn) * scr;
;             }
;           }
;           u32x4 w1, w2;
;           w1.x = pk(y1[0], y1[1]); w1.y = pk(y1[2], y1[3]); w1.z = pk(y1[4], y1[5]); w1.w = pk(y1[6], y1[7]);
;           w2.x = pk(y2[0], y2[1]); w2.y = pk(y2[2], y2[3]); w2.z = pk(y2[4], y2[5]); w2.w = pk(y2[6], y2[7]);
;           bf16_t* op = g.o0 + (size_t)row * 2048 + bcol + d0;
;           gst<u32x4>(op, w1); gst<u32x4>(op + 128, w2);
	v_pk_mul_f32 v[178:179], v[128:129], v[178:179] op_sel_hi:[0,1]
	v_pk_fma_f32 v[130:131], v[106:107], v[130:131], v[176:177]
	s_nop 0
	v_pk_mul_f32 v[176:177], v[128:129], v[130:131] op_sel_hi:[0,1]
	v_cvt_pk_bf16_f32 v128, v134, v135
	v_cvt_pk_bf16_f32 v129, v170, v171
	v_cvt_pk_bf16_f32 v130, v174, v175
	v_cvt_pk_bf16_f32 v131, v178, v179
	v_cvt_pk_bf16_f32 v134, v172, v173
	v_cvt_pk_bf16_f32 v135, v176, v177
	global_store_dwordx4 v[142:143], v[128:131], off
	global_store_dwordx4 v[142:143], v[132:135], off offset:256
	s_nop 1
	v_mov_b32_e32 v128, v239
	v_or_b32_e32 v142, 48, v166
	v_ashrrev_i32_e32 v143, 31, v142
	v_lshlrev_b64 v[142:143], 12, v[142:143]
	v_lshl_add_u64 v[142:143], s[64:65], 0, v[142:143]
	v_lshl_add_u64 v[142:143], v[142:143], 0, s[26:27]
	v_lshl_add_u64 v[142:143], v[142:143], 0, v[148:149]
	s_mov_b64 s[26:27], 0x80000
	v_cvt_f32_i32_e32 v129, v128
	s_nop 1
	v_mov_b32_e32 v128, v247
	v_mul_f32_e32 v130, v220, v129
	v_rndne_f32_e32 v130, v130
	v_fma_f32 v131, v220, v129, -v130
	v_sin_f32_e32 v130, v131
	v_cos_f32_e32 v132, v131
	v_mul_f32_e32 v131, v221, v129
	v_rndne_f32_e32 v131, v131
	v_fma_f32 v133, v221, v129, -v131
	v_sin_f32_e32 v131, v133
	v_cos_f32_e32 v133, v133
	v_pk_mul_f32 v[134:135], v[36:37], v[130:131]
	v_pk_mul_f32 v[130:131], v[100:101], v[130:131]
	v_pk_fma_f32 v[134:135], v[100:101], v[132:133], v[134:135] neg_lo:[0,0,1] neg_hi:[0,0,1]
	v_pk_fma_f32 v[130:131], v[36:37], v[132:133], v[130:131]
	v_mul_f32_e32 v128, v165, v128
	v_pk_mul_f32 v[132:133], v[128:129], v[130:131] op_sel_hi:[0,1]
	v_mul_f32_e32 v130, v222, v129
	v_rndne_f32_e32 v130, v130
	v_fma_f32 v131, v222, v129, -v130
	v_sin_f32_e32 v130, v131
	v_cos_f32_e32 v168, v131
	v_mul_f32_e32 v131, v223, v129
	v_rndne_f32_e32 v131, v131
	v_fma_f32 v167, v223, v129, -v131
	v_sin_f32_e32 v131, v167
	v_cos_f32_e32 v169, v167
	v_pk_mul_f32 v[134:135], v[128:129], v[134:135] op_sel_hi:[0,1]
	v_cvt_pk_bf16_f32 v132, v132, v133
	v_pk_mul_f32 v[170:171], v[38:39], v[130:131]
	v_pk_mul_f32 v[130:131], v[102:103], v[130:131]
	v_pk_fma_f32 v[170:171], v[102:103], v[168:169], v[170:171] neg_lo:[0,0,1] neg_hi:[0,0,1]
	v_pk_fma_f32 v[130:131], v[38:39], v[168:169], v[130:131]
	v_pk_mul_f32 v[170:171], v[128:129], v[170:171] op_sel_hi:[0,1]
	v_pk_mul_f32 v[168:169], v[128:129], v[130:131] op_sel_hi:[0,1]
	v_mul_f32_e32 v130, v224, v129
	v_rndne_f32_e32 v130, v130
	v_fma_f32 v131, v224, v129, -v130
	v_sin_f32_e32 v130, v131
	v_cos_f32_e32 v172, v131
	v_mul_f32_e32 v131, v225, v129
	v_rndne_f32_e32 v131, v131
	v_fma_f32 v167, v225, v129, -v131
	v_sin_f32_e32 v131, v167
	v_cos_f32_e32 v173, v167
	v_cvt_pk_bf16_f32 v133, v168, v169
	v_pk_mul_f32 v[174:175], v[32:33], v[130:131]
	s_nop 0
	v_pk_fma_f32 v[174:175], v[96:97], v[172:173], v[174:175] neg_lo:[0,0,1] neg_hi:[0,0,1]
	v_pk_mul_f32 v[172:173], v[32:33], v[172:173]
	v_pk_mul_f32 v[174:175], v[128:129], v[174:175] op_sel_hi:[0,1]
	v_pk_fma_f32 v[130:131], v[96:97], v[130:131], v[172:173]
	s_nop 0
	v_pk_mul_f32 v[172:173], v[128:129], v[130:131] op_sel_hi:[0,1]
	v_mul_f32_e32 v130, v226, v129
	v_rndne_f32_e32 v130, v130
	v_fma_f32 v131, v226, v129, -v130
	v_sin_f32_e32 v130, v131
	v_cos_f32_e32 v176, v131
	v_mul_f32_e32 v131, v227, v129
	v_rndne_f32_e32 v131, v131
	v_fma_f32 v129, v227, v129, -v131
	v_sin_f32_e32 v131, v129
	v_cos_f32_e32 v177, v129
	v_pk_mul_f32 v[178:179], v[34:35], v[130:131]
	s_nop 0
	v_pk_fma_f32 v[178:179], v[98:99], v[176:177], v[178:179] neg_lo:[0,0,1] neg_hi:[0,0,1]
	v_pk_mul_f32 v[176:177], v[34:35], v[176:177]
	v_pk_mul_f32 v[178:179], v[128:129], v[178:179] op_sel_hi:[0,1]
	v_pk_fma_f32 v[130:131], v[98:99], v[130:131], v[176:177]
	s_nop 0
	v_pk_mul_f32 v[176:177], v[128:129], v[130:131] op_sel_hi:[0,1]
	v_cvt_pk_bf16_f32 v128, v134, v135
	v_cvt_pk_bf16_f32 v129, v170, v171
	v_cvt_pk_bf16_f32 v130, v174, v175
	v_cvt_pk_bf16_f32 v131, v178, v179
	v_cvt_pk_bf16_f32 v134, v172, v173
	v_cvt_pk_bf16_f32 v135, v176, v177
	global_store_dwordx4 v[142:143], v[128:131], off
	global_store_dwordx4 v[142:143], v[132:135], off offset:256
	s_nop 1
	v_mov_b32_e32 v128, v240
	v_cvt_f32_i32_e32 v129, v128
	s_nop 1
	v_mov_b32_e32 v128, v248
	v_mul_f32_e32 v130, v220, v129
	v_rndne_f32_e32 v130, v130
	v_fma_f32 v131, v220, v129, -v130
	v_sin_f32_e32 v130, v131
	v_cos_f32_e32 v132, v131
	v_mul_f32_e32 v131, v221, v129
	v_rndne_f32_e32 v131, v131
	v_fma_f32 v133, v221, v129, -v131
	v_sin_f32_e32 v131, v133
	v_cos_f32_e32 v133, v133
	v_pk_mul_f32 v[134:135], v[28:29], v[130:131]
	v_pk_mul_f32 v[130:131], v[92:93], v[130:131]
	v_pk_fma_f32 v[134:135], v[92:93], v[132:133], v[134:135] neg_lo:[0,0,1] neg_hi:[0,0,1]
	v_pk_fma_f32 v[130:131], v[28:29], v[132:133], v[130:131]
	v_mul_f32_e32 v128, v165, v128
	v_pk_mul_f32 v[132:133], v[128:129], v[130:131] op_sel_hi:[0,1]
	v_mul_f32_e32 v130, v222, v129
	v_rndne_f32_e32 v130, v130
	v_fma_f32 v131, v222, v129, -v130
	v_sin_f32_e32 v130, v131
	v_cos_f32_e32 v142, v131
	v_mul_f32_e32 v131, v223, v129
	v_rndne_f32_e32 v131, v131
	v_fma_f32 v143, v223, v129, -v131
	v_sin_f32_e32 v131, v143
	v_cos_f32_e32 v143, v143
	v_pk_mul_f32 v[134:135], v[128:129], v[134:135] op_sel_hi:[0,1]
	v_cvt_pk_bf16_f32 v132, v132, v133
	v_pk_mul_f32 v[168:169], v[30:31], v[130:131]
	v_pk_mul_f32 v[130:131], v[94:95], v[130:131]
	v_pk_fma_f32 v[168:169], v[94:95], v[142:143], v[168:169] neg_lo:[0,0,1] neg_hi:[0,0,1]
	v_pk_fma_f32 v[130:131], v[30:31], v[142:143], v[130:131]
	v_pk_mul_f32 v[168:169], v[128:129], v[168:169] op_sel_hi:[0,1]
	v_pk_mul_f32 v[142:143], v[128:129], v[130:131] op_sel_hi:[0,1]
	v_mul_f32_e32 v130, v224, v129
	v_rndne_f32_e32 v130, v130
	v_fma_f32 v131, v224, v129, -v130
; DI unsigned pk(float lo, float hi) { f32x2 v = {lo, hi}; bf2_t b = __builtin_convertvector(v, bf2_t); return __builtin_bit_cast(unsigned, b); }
; DI void gemm_epilogue(const GemmDesc& g, f32x4 (&acc)[2][2][4][2], int brow, int bcol, int wr, int wc, int fr, int fq) {
;     ...
;           const int row = rowb + ai * HALF + m * 16;
;           const float pf = (float)gld<int>(g.pos + row);
;           const float scr = sc * gld<float>(g.rowscale + row);
;           float y1[8], y2[8];
; #pragma unroll
;           for (int n = 0; n < 2; ++n) {
;             const f32x4 x1 = acc[ai][0][m][n], x2 = acc[ai][1][m][n];
; #pragma unroll
;             for (int j = 0; j < 4; ++j) {
;               float rev = pf * fr_[4 * n + j]; rev = rev - rintf(rev);
;               const float sn = __builtin_amdgcn_sinf(rev), cs = __builtin_amdgcn_cosf(rev);
;               y1[4 * n + j] = (x1[j] * cs - x2[j] * sn) * scr; y2[4 * n + j] = (x2[j] * cs + x1[j] * sn) * scr;
;             }
;           }
;           u32x4 w1, w2;
;           w1.x = pk(y1[0], y1[1]); w1.y = pk(y1[2], y1[3]); w1.z = pk(y1[4], y1[5]); w1.w = pk(y1[6], y1[7]);
;           w2.x = pk(y2[0], y2[1]); w2.y = pk(y2[2], y2[3]); w2.z = pk(y2[4], y2[5]); w2.w = pk(y2[6], y2[7]);
;           bf16_t* op = g.o0 + (size_t)row * 2048 + bcol + d0;
;           gst<u32x4>(op, w1); gst<u32x4>(op + 128, w2);
	v_sin_f32_e32 v130, v131
	v_cos_f32_e32 v170, v131
	v_mul_f32_e32 v131, v225, v129
	v_rndne_f32_e32 v131, v131
	v_fma_f32 v148, v225, v129, -v131
	v_sin_f32_e32 v131, v148
	v_cos_f32_e32 v171, v148
	v_cvt_pk_bf16_f32 v133, v142, v143
	v_lshl_add_u64 v[142:143], v[140:141], 0, s[26:27]
	v_pk_mul_f32 v[172:173], v[24:25], v[130:131]
	s_mov_b64 s[26:27], 0x90000
	v_pk_fma_f32 v[172:173], v[88:89], v[170:171], v[172:173] neg_lo:[0,0,1] neg_hi:[0,0,1]
	v_pk_mul_f32 v[170:171], v[24:25], v[170:171]
	v_pk_mul_f32 v[172:173], v[128:129], v[172:173] op_sel_hi:[0,1]
	v_pk_fma_f32 v[130:131], v[88:89], v[130:131], v[170:171]
	s_nop 0
	v_pk_mul_f32 v[170:171], v[128:129], v[130:131] op_sel_hi:[0,1]
	v_mul_f32_e32 v130, v226, v129
	v_rndne_f32_e32 v130, v130
	v_fma_f32 v131, v226, v129, -v130
	v_sin_f32_e32 v130, v131
	v_cos_f32_e32 v174, v131
	v_mul_f32_e32 v131, v227, v129
	v_rndne_f32_e32 v131, v131
	v_fma_f32 v129, v227, v129, -v131
	v_sin_f32_e32 v131, v129
	v_cos_f32_e32 v175, v129
	v_pk_mul_f32 v[176:177], v[26:27], v[130:131]
	s_nop 0
	v_pk_fma_f32 v[176:177], v[90:91], v[174:175], v[176:177] neg_lo:[0,0,1] neg_hi:[0,0,1]
	v_pk_mul_f32 v[174:175], v[26:27], v[174:175]
	v_pk_mul_f32 v[176:177], v[128:129], v[176:177] op_sel_hi:[0,1]
	v_pk_fma_f32 v[130:131], v[90:91], v[130:131], v[174:175]
	s_nop 0
	v_pk_mul_f32 v[174:175], v[128:129], v[130:131] op_sel_hi:[0,1]
	v_cvt_pk_bf16_f32 v129, v168, v169
	v_add_co_u32_e32 v168, vcc, s5, v140
	v_cvt_pk_bf16_f32 v128, v134, v135
	v_cvt_pk_bf16_f32 v130, v172, v173
	v_cvt_pk_bf16_f32 v131, v176, v177
	v_addc_co_u32_e32 v169, vcc, 0, v141, vcc
	v_cvt_pk_bf16_f32 v134, v170, v171
	v_cvt_pk_bf16_f32 v135, v174, v175
	global_store_dwordx4 v[168:169], v[128:131], off
	global_store_dwordx4 v[142:143], v[132:135], off offset:256
	s_nop 1
	v_mov_b32_e32 v128, v241
	s_mov_b32 s5, 0x90000
	v_cvt_f32_i32_e32 v129, v128
	s_nop 1
	v_mov_b32_e32 v128, v249
	v_mul_f32_e32 v130, v220, v129
	v_rndne_f32_e32 v130, v130
	v_fma_f32 v131, v220, v129, -v130
	v_sin_f32_e32 v130, v131
	v_cos_f32_e32 v132, v131
	v_mul_f32_e32 v131, v221, v129
	v_rndne_f32_e32 v131, v131
	v_fma_f32 v133, v221, v129, -v131
	v_sin_f32_e32 v131, v133
	v_cos_f32_e32 v133, v133
	v_pk_mul_f32 v[134:135], v[20:21], v[130:131]
	v_pk_mul_f32 v[130:131], v[84:85], v[130:131]
	v_pk_fma_f32 v[134:135], v[84:85], v[132:133], v[134:135] neg_lo:[0,0,1] neg_hi:[0,0,1]
	v_pk_fma_f32 v[130:131], v[20:21], v[132:133], v[130:131]
	v_mul_f32_e32 v128, v165, v128
	v_pk_mul_f32 v[132:133], v[128:129], v[130:131] op_sel_hi:[0,1]
	v_mul_f32_e32 v130, v222, v129
	v_rndne_f32_e32 v130, v130
	v_fma_f32 v131, v222, v129, -v130
	v_sin_f32_e32 v130, v131
	v_cos_f32_e32 v142, v131
	v_mul_f32_e32 v131, v223, v129
	v_rndne_f32_e32 v131, v131
	v_fma_f32 v143, v223, v129, -v131
	v_sin_f32_e32 v131, v143
	v_cos_f32_e32 v143, v143
	v_pk_mul_f32 v[134:135], v[128:129], v[134:135] op_sel_hi:[0,1]
	v_cvt_pk_bf16_f32 v132, v132, v133
	v_pk_mul_f32 v[168:169], v[22:23], v[130:131]
	v_pk_mul_f32 v[130:131], v[86:87], v[130:131]
	v_pk_fma_f32 v[168:169], v[86:87], v[142:143], v[168:169] neg_lo:[0,0,1] neg_hi:[0,0,1]
	v_pk_fma_f32 v[130:131], v[22:23], v[142:143], v[130:131]
	v_pk_mul_f32 v[168:169], v[128:129], v[168:169] op_sel_hi:[0,1]
	v_pk_mul_f32 v[142:143], v[128:129], v[130:131] op_sel_hi:[0,1]
	v_mul_f32_e32 v130, v224, v129
	v_rndne_f32_e32 v130, v130
	v_fma_f32 v131, v224, v129, -v130
	v_sin_f32_e32 v130, v131
	v_cos_f32_e32 v170, v131
	v_mul_f32_e32 v131, v225, v129
	v_rndne_f32_e32 v131, v131
	v_fma_f32 v148, v225, v129, -v131
	v_sin_f32_e32 v131, v148
	v_cos_f32_e32 v171, v148
	v_cvt_pk_bf16_f32 v133, v142, v143
	v_lshl_add_u64 v[142:143], v[140:141], 0, s[26:27]
	v_pk_mul_f32 v[172:173], v[16:17], v[130:131]
	s_mov_b64 s[26:27], 0xa0000
	v_pk_fma_f32 v[172:173], v[80:81], v[170:171], v[172:173] neg_lo:[0,0,1] neg_hi:[0,0,1]
	v_pk_mul_f32 v[170:171], v[16:17], v[170:171]
	v_pk_mul_f32 v[172:173], v[128:129], v[172:173] op_sel_hi:[0,1]
	v_pk_fma_f32 v[130:131], v[80:81], v[130:131], v[170:171]
	s_nop 0
	v_pk_mul_f32 v[170:171], v[128:129], v[130:131] op_sel_hi:[0,1]
	v_mul_f32_e32 v130, v226, v129
	v_rndne_f32_e32 v130, v130
	v_fma_f32 v131, v226, v129, -v130
	v_sin_f32_e32 v130, v131
	v_cos_f32_e32 v174, v131
	v_mul_f32_e32 v131, v227, v129
	v_rndne_f32_e32 v131, v131
	v_fma_f32 v129, v227, v129, -v131
	v_sin_f32_e32 v131, v129
	v_cos_f32_e32 v175, v129
	v_pk_mul_f32 v[176:177], v[18:19], v[130:131]
	s_nop 0
	v_pk_fma_f32 v[176:177], v[82:83], v[174:175], v[176:177] neg_lo:[0,0,1] neg_hi:[0,0,1]
	v_pk_mul_f32 v[174:175], v[18:19], v[174:175]
	v_pk_mul_f32 v[176:177], v[128:129], v[176:177] op_sel_hi:[0,1]
	v_pk_fma_f32 v[130:131], v[82:83], v[130:131], v[174:175]
	s_nop 0
	v_pk_mul_f32 v[174:175], v[128:129], v[130:131] op_sel_hi:[0,1]
	v_cvt_pk_bf16_f32 v129, v168, v169
	v_add_co_u32_e32 v168, vcc, s5, v140
	v_cvt_pk_bf16_f32 v128, v134, v135
	v_cvt_pk_bf16_f32 v130, v172, v173
	v_cvt_pk_bf16_f32 v131, v176, v177
	v_addc_co_u32_e32 v169, vcc, 0, v141, vcc
	v_cvt_pk_bf16_f32 v134, v170, v171
	v_cvt_pk_bf16_f32 v135, v174, v175
	global_store_dwordx4 v[168:169], v[128:131], off
	global_store_dwordx4 v[142:143], v[132:135], off offset:256
	s_nop 1
	v_mov_b32_e32 v128, v242
	s_mov_b32 s5, 0xa0000
	v_cvt_f32_i32_e32 v129, v128
	s_nop 1
	v_mov_b32_e32 v128, v251
	v_mul_f32_e32 v130, v220, v129
	v_rndne_f32_e32 v130, v130
	v_fma_f32 v131, v220, v129, -v130
	v_sin_f32_e32 v130, v131
	v_cos_f32_e32 v132, v131
	v_mul_f32_e32 v131, v221, v129
	v_rndne_f32_e32 v131, v131
	v_fma_f32 v133, v221, v129, -v131
	v_sin_f32_e32 v131, v133
	v_cos_f32_e32 v133, v133
	v_pk_mul_f32 v[134:135], v[12:13], v[130:131]
; DI unsigned pk(float lo, float hi) { f32x2 v = {lo, hi}; bf2_t b = __builtin_convertvector(v, bf2_t); return __builtin_bit_cast(unsigned, b); }
; DI void gemm_epilogue(const GemmDesc& g, f32x4 (&acc)[2][2][4][2], int brow, int bcol, int wr, int wc, int fr, int fq) {
;     ...
;           const int row = rowb + ai * HALF + m * 16;
;           const float pf = (float)gld<int>(g.pos + row);
;           const float scr = sc * gld<float>(g.rowscale + row);
;           float y1[8], y2[8];
; #pragma unroll
;           for (int n = 0; n < 2; ++n) {
;             const f32x4 x1 = acc[ai][0][m][n], x2 = acc[ai][1][m][n];
; #pragma unroll
;             for (int j = 0; j < 4; ++j) {
;               float rev = pf * fr_[4 * n + j]; rev = rev - rintf(rev);
;               const float sn = __builtin_amdgcn_sinf(rev), cs = __builtin_amdgcn_cosf(rev);
;               y1[4 * n + j] = (x1[j] * cs - x2[j] * sn) * scr; y2[4 * n + j] = (x2[j] * cs + x1[j] * sn) * scr;
;             }
;           }
;           u32x4 w1, w2;
;           w1.x = pk(y1[0], y1[1]); w1.y = pk(y1[2], y1[3]); w1.z = pk(y1[4], y1[5]); w1.w = pk(y1[6], y1[7]);
;           w2.x = pk(y2[0], y2[1]); w2.y = pk(y2[2], y2[3]); w2.z = pk(y2[4], y2[5]); w2.w = pk(y2[6], y2[7]);
;           bf16_t* op = g.o0 + (size_t)row * 2048 + bcol + d0;
;           gst<u32x4>(op, w1); gst<u32x4>(op + 128, w2);
	v_pk_mul_f32 v[130:131], v[76:77], v[130:131]
	v_pk_fma_f32 v[134:135], v[76:77], v[132:133], v[134:135] neg_lo:[0,0,1] neg_hi:[0,0,1]
	v_pk_fma_f32 v[130:131], v[12:13], v[132:133], v[130:131]
	v_mul_f32_e32 v128, v165, v128
	v_pk_mul_f32 v[132:133], v[128:129], v[130:131] op_sel_hi:[0,1]
	v_mul_f32_e32 v130, v222, v129
	v_rndne_f32_e32 v130, v130
	v_fma_f32 v131, v222, v129, -v130
	v_sin_f32_e32 v130, v131
	v_cos_f32_e32 v142, v131
	v_mul_f32_e32 v131, v223, v129
	v_rndne_f32_e32 v131, v131
	v_fma_f32 v143, v223, v129, -v131
	v_sin_f32_e32 v131, v143
	v_cos_f32_e32 v143, v143
	v_pk_mul_f32 v[134:135], v[128:129], v[134:135] op_sel_hi:[0,1]
	v_cvt_pk_bf16_f32 v132, v132, v133
	v_pk_mul_f32 v[168:169], v[14:15], v[130:131]
	v_pk_mul_f32 v[130:131], v[78:79], v[130:131]
	v_pk_fma_f32 v[168:169], v[78:79], v[142:143], v[168:169] neg_lo:[0,0,1] neg_hi:[0,0,1]
	v_pk_fma_f32 v[130:131], v[14:15], v[142:143], v[130:131]
	v_pk_mul_f32 v[168:169], v[128:129], v[168:169] op_sel_hi:[0,1]
	v_pk_mul_f32 v[142:143], v[128:129], v[130:131] op_sel_hi:[0,1]
	v_mul_f32_e32 v130, v224, v129
	v_rndne_f32_e32 v130, v130
	v_fma_f32 v131, v224, v129, -v130
	v_sin_f32_e32 v130, v131
	v_cos_f32_e32 v170, v131
	v_mul_f32_e32 v131, v225, v129
	v_rndne_f32_e32 v131, v131
	v_fma_f32 v148, v225, v129, -v131
	v_sin_f32_e32 v131, v148
	v_cos_f32_e32 v171, v148
	v_cvt_pk_bf16_f32 v133, v142, v143
	v_lshl_add_u64 v[142:143], v[140:141], 0, s[26:27]
	v_pk_mul_f32 v[172:173], v[8:9], v[130:131]
	s_mov_b64 s[26:27], 0xb0000
	v_pk_fma_f32 v[172:173], v[72:73], v[170:171], v[172:173] neg_lo:[0,0,1] neg_hi:[0,0,1]
	v_pk_mul_f32 v[170:171], v[8:9], v[170:171]
	v_pk_mul_f32 v[172:173], v[128:129], v[172:173] op_sel_hi:[0,1]
	v_pk_fma_f32 v[130:131], v[72:73], v[130:131], v[170:171]
	s_nop 0
	v_pk_mul_f32 v[170:171], v[128:129], v[130:131] op_sel_hi:[0,1]
	v_mul_f32_e32 v130, v226, v129
	v_rndne_f32_e32 v130, v130
	v_fma_f32 v131, v226, v129, -v130
	v_sin_f32_e32 v130, v131
	v_cos_f32_e32 v174, v131
	v_mul_f32_e32 v131, v227, v129
	v_rndne_f32_e32 v131, v131
	v_fma_f32 v129, v227, v129, -v131
	v_sin_f32_e32 v131, v129
	v_cos_f32_e32 v175, v129
	v_pk_mul_f32 v[176:177], v[10:11], v[130:131]
	s_nop 0
	v_pk_fma_f32 v[176:177], v[74:75], v[174:175], v[176:177] neg_lo:[0,0,1] neg_hi:[0,0,1]
	v_pk_mul_f32 v[174:175], v[10:11], v[174:175]
	v_pk_mul_f32 v[176:177], v[128:129], v[176:177] op_sel_hi:[0,1]
	v_pk_fma_f32 v[130:131], v[74:75], v[130:131], v[174:175]
	s_nop 0
	v_pk_mul_f32 v[174:175], v[128:129], v[130:131] op_sel_hi:[0,1]
	v_cvt_pk_bf16_f32 v129, v168, v169
	v_add_co_u32_e32 v168, vcc, s5, v140
	v_cvt_pk_bf16_f32 v128, v134, v135
	v_cvt_pk_bf16_f32 v130, v172, v173
	v_cvt_pk_bf16_f32 v131, v176, v177
	v_addc_co_u32_e32 v169, vcc, 0, v141, vcc
	v_cvt_pk_bf16_f32 v134, v170, v171
	v_cvt_pk_bf16_f32 v135, v174, v175
	global_store_dwordx4 v[168:169], v[128:131], off
	global_store_dwordx4 v[142:143], v[132:135], off offset:256
	s_nop 1
	v_mov_b32_e32 v128, v243
	v_cvt_f32_i32_e32 v129, v128
	s_nop 1
	v_mov_b32_e32 v128, v252
	v_mul_f32_e32 v130, v220, v129
	v_rndne_f32_e32 v130, v130
	v_fma_f32 v131, v220, v129, -v130
	v_sin_f32_e32 v130, v131
	v_cos_f32_e32 v132, v131
	v_mul_f32_e32 v131, v221, v129
	v_rndne_f32_e32 v131, v131
	v_fma_f32 v133, v221, v129, -v131
	v_sin_f32_e32 v131, v133
	v_cos_f32_e32 v133, v133
	v_pk_mul_f32 v[134:135], v[4:5], v[130:131]
	v_pk_mul_f32 v[130:131], v[68:69], v[130:131]
	v_pk_fma_f32 v[134:135], v[68:69], v[132:133], v[134:135] neg_lo:[0,0,1] neg_hi:[0,0,1]
	v_pk_fma_f32 v[130:131], v[4:5], v[132:133], v[130:131]
	v_mul_f32_e32 v128, v165, v128
	v_pk_mul_f32 v[132:133], v[128:129], v[130:131] op_sel_hi:[0,1]
	v_mul_f32_e32 v130, v222, v129
	v_rndne_f32_e32 v130, v130
	v_fma_f32 v131, v222, v129, -v130
	v_sin_f32_e32 v130, v131
	v_cos_f32_e32 v136, v131
	v_mul_f32_e32 v131, v223, v129
	v_rndne_f32_e32 v131, v131
	v_fma_f32 v137, v223, v129, -v131
	v_sin_f32_e32 v131, v137
	v_cos_f32_e32 v137, v137
	v_pk_mul_f32 v[134:135], v[128:129], v[134:135] op_sel_hi:[0,1]
	v_cvt_pk_bf16_f32 v132, v132, v133
	v_pk_mul_f32 v[138:139], v[6:7], v[130:131]
	v_pk_mul_f32 v[130:131], v[70:71], v[130:131]
	v_pk_fma_f32 v[138:139], v[70:71], v[136:137], v[138:139] neg_lo:[0,0,1] neg_hi:[0,0,1]
	v_pk_fma_f32 v[130:131], v[6:7], v[136:137], v[130:131]
	v_pk_mul_f32 v[138:139], v[128:129], v[138:139] op_sel_hi:[0,1]
	v_pk_mul_f32 v[136:137], v[128:129], v[130:131] op_sel_hi:[0,1]
	v_mul_f32_e32 v130, v224, v129
	v_rndne_f32_e32 v130, v130
	v_fma_f32 v131, v224, v129, -v130
	v_sin_f32_e32 v130, v131
	v_cos_f32_e32 v142, v131
	v_mul_f32_e32 v131, v225, v129
	v_rndne_f32_e32 v131, v131
	v_fma_f32 v143, v225, v129, -v131
	v_sin_f32_e32 v131, v143
	v_cos_f32_e32 v143, v143
	v_cvt_pk_bf16_f32 v133, v136, v137
	v_lshl_add_u64 v[136:137], v[140:141], 0, s[26:27]
	v_pk_mul_f32 v[168:169], v[0:1], v[130:131]
	s_nop 0
	v_pk_fma_f32 v[168:169], v[64:65], v[142:143], v[168:169] neg_lo:[0,0,1] neg_hi:[0,0,1]
	v_pk_mul_f32 v[142:143], v[0:1], v[142:143]
	v_pk_mul_f32 v[168:169], v[128:129], v[168:169] op_sel_hi:[0,1]
	v_pk_fma_f32 v[130:131], v[64:65], v[130:131], v[142:143]
	s_nop 0
	v_pk_mul_f32 v[142:143], v[128:129], v[130:131] op_sel_hi:[0,1]
	v_mul_f32_e32 v130, v226, v129
	v_rndne_f32_e32 v130, v130
	v_fma_f32 v131, v226, v129, -v130
	v_sin_f32_e32 v130, v131
	v_cos_f32_e32 v170, v131
	v_mul_f32_e32 v131, v227, v129
	v_rndne_f32_e32 v131, v131
	v_fma_f32 v129, v227, v129, -v131
	v_sin_f32_e32 v131, v129
	v_cos_f32_e32 v171, v129
	v_pk_mul_f32 v[172:173], v[2:3], v[130:131]
	s_nop 0
	v_pk_fma_f32 v[172:173], v[66:67], v[170:171], v[172:173] neg_lo:[0,0,1] neg_hi:[0,0,1]
	v_pk_mul_f32 v[170:171], v[2:3], v[170:171]
	v_pk_mul_f32 v[172:173], v[128:129], v[172:173] op_sel_hi:[0,1]
	v_pk_fma_f32 v[130:131], v[66:67], v[130:131], v[170:171]
	s_nop 0
	v_pk_mul_f32 v[170:171], v[128:129], v[130:131] op_sel_hi:[0,1]
	v_cvt_pk_bf16_f32 v129, v138, v139
	v_add_co_u32_e32 v138, vcc, 0xb0000, v140
	v_cvt_pk_bf16_f32 v128, v134, v135
	v_cvt_pk_bf16_f32 v130, v168, v169
	v_cvt_pk_bf16_f32 v131, v172, v173
	v_addc_co_u32_e32 v139, vcc, 0, v141, vcc
	v_cvt_pk_bf16_f32 v134, v142, v143
	v_cvt_pk_bf16_f32 v135, v170, v171
	global_store_dwordx4 v[138:139], v[128:131], off
	global_store_dwordx4 v[136:137], v[132:135], off offset:256
	s_branch .LBB0_423
